# first K-iteration of each unit: leading vmcnt waits relaxed by the number of epilogue stores so the store drain overlaps the first MFMA segments (in-proj, gate-up)
# speedup vs baseline: 1.0057x; 1.0009x over previous
; #define PG8_STAGE(bufoff, gbase, voff) do { _Pragma("unroll") for (int _i = 0; _i < 2; ++_i) \
;         __builtin_amdgcn_global_load_lds((const unsigned*)((const char*)(gbase) + (voff)[_i]), (LAS unsigned*)(lds + (bufoff) + ldsw + _i * 8192), 16, 0, 0); } while (0)
; #define PG8_LDA(dst, b, h) do { _Pragma("unroll") for (int m = 0; m < 4; ++m) _Pragma("unroll") for (int k = 0; k < 2; ++k) dst[m][k] = *(const LAS bf16x8*)(lds + PG8_SA(b, h) + aoff + m * 2048 + k * 1024); } while (0)
; #define PG8_LDB(dst, b, h) do { _Pragma("unroll") for (int n = 0; n < 2; ++n) _Pragma("unroll") for (int k = 0; k < 2; ++k) dst[n][k] = *(const LAS bf16x8*)(lds + PG8_SB(b, h) + boff + n * 2048 + k * 1024); } while (0)
; #define PG8_MMA(ai, bj, At, Bt) do { __builtin_amdgcn_s_setprio(1); _Pragma("unroll") for (int m = 0; m < 4; ++m) _Pragma("unroll") for (int n = 0; n < 2; ++n) _Pragma("unroll") for (int k = 0; k < 2; ++k) \
;         acc[ai][bj][m][n] = __builtin_amdgcn_mfma_f32_16x16x32_bf16(Bt[n][k], At[m][k], acc[ai][bj][m][n], 0, 0, 0); __builtin_amdgcn_s_setprio(0); } while (0)
; #define PG8_WAIT_V(n) asm volatile("s_waitcnt vmcnt(" #n ")" ::: "memory")
; #define PG8_WAIT_L(n) asm volatile("s_waitcnt lgkmcnt(" #n ")" ::: "memory")
; #define PG8_BAR __builtin_amdgcn_s_barrier()
; template <int KK, class Epi, class Sched, bool ALIGN_EPI = true>
; __device__ __forceinline__ void gemm_phase(LAS unsigned char* lds, const bf16* gA, const bf16* gBt, const Sched& S, const Epi& E, const int wid) {
;     ...
;         for (int t = 0; t < nt; t += 2) {
;             const bool last = (t == nt - 2);
;             const char* a1 = cA + (size_t)(t + 1) * kstep;
;             const char* a2 = last ? nA : cA + (size_t)(t + 2) * kstep; const char* b2 = last ? nB : cB + (size_t)(t + 2) * kstep;
;             const char* a3 = a2 + kstep; const char* b3 = b2 + kstep;
;             PG8_LDB(B0, 0, 0); PG8_LDB(B1, 0, 1); PG8_SCHED; PG8_LDA(At, 0, 0); PG8_STAGE(PG8_SA(1, 1), a1 + hstep, voffA);
;             PG8_WAIT_V(8); PG8_WAIT_L(0); PG8_BAR; PG8_MMA(0, 0, At, B0); PG8_MMA(0, 1, At, B1); PG8_BAR; PG8_SCHED;
;             PG8_LDA(At, 0, 1); PG8_STAGE(PG8_SB(0, 0), b2, voffB); PG8_STAGE(PG8_SB(0, 1), b2 + hstep, voffB); PG8_STAGE(PG8_SA(0, 0), a2, voffA);
;             PG8_WAIT_V(8); PG8_WAIT_L(0); PG8_BAR; PG8_MMA(1, 0, At, B0); PG8_MMA(1, 1, At, B1); PG8_BAR; PG8_SCHED;
.LBB0_155:
	ds_read_b128 v[144:147], v169
	ds_read_b128 v[148:151], v169 offset:1024
	ds_read_b128 v[152:155], v169 offset:2048
	ds_read_b128 v[156:159], v169 offset:3072
	ds_read_b128 v[160:163], v170
	ds_read_b128 v[176:179], v170 offset:1024
	ds_read_b128 v[180:183], v170 offset:2048
	ds_read_b128 v[184:187], v170 offset:3072
	s_add_u32 s6, s4, 0xfffc0080
	s_addc_u32 s7, s5, -1
	s_cmp_eq_u32 s31, 12
	s_cselect_b32 s9, s10, s7
	s_cselect_b32 s8, s11, s6
	s_cselect_b32 s7, s13, s30
	s_cselect_b32 s6, s14, s15
	v_lshl_add_u64 v[164:165], s[4:5], 0, v[140:141]
	s_add_i32 m0, s77, 0xc000
	ds_read_b128 v[188:191], v171
	ds_read_b128 v[192:195], v171 offset:1024
	ds_read_b128 v[198:201], v171 offset:2048
	ds_read_b128 v[202:205], v171 offset:3072
	ds_read_b128 v[206:209], v171 offset:4096
	ds_read_b128 v[210:213], v171 offset:5120
	ds_read_b128 v[214:217], v171 offset:6144
	ds_read_b128 v[218:221], v171 offset:7168
	global_load_lds_dwordx4 v[164:165], off
	v_lshl_add_u64 v[164:165], s[4:5], 0, v[138:139]
	s_add_i32 m0, s77, 0xe000
	s_nop 0
	global_load_lds_dwordx4 v[164:165], off
	s_cmp_lg_u32 s31, -2
	s_cbranch_scc1 .Lfw1a0_st
	s_cmp_eq_u32 s85, 1
	s_cbranch_scc1 .Lfw1a0_st
	s_waitcnt vmcnt(24)
	s_branch .Lfw1a0_dn
.Lfw1a0_st:
	s_waitcnt vmcnt(8)
.Lfw1a0_dn:
	s_waitcnt lgkmcnt(0)
	s_barrier
	s_setprio 1
	s_waitcnt lgkmcnt(0)
	v_mfma_f32_16x16x32_bf16 v[124:127], v[144:147], v[188:191], v[124:127]
	v_mfma_f32_16x16x32_bf16 v[120:123], v[152:155], v[188:191], v[120:123]
	v_mfma_f32_16x16x32_bf16 v[108:111], v[144:147], v[198:201], v[108:111]
	v_mfma_f32_16x16x32_bf16 v[104:107], v[152:155], v[198:201], v[104:107]
	v_mfma_f32_16x16x32_bf16 v[92:95], v[144:147], v[206:209], v[92:95]
	v_mfma_f32_16x16x32_bf16 v[88:91], v[152:155], v[206:209], v[88:91]
	v_mfma_f32_16x16x32_bf16 v[76:79], v[144:147], v[214:217], v[76:79]
	v_mfma_f32_16x16x32_bf16 v[72:75], v[152:155], v[214:217], v[72:75]
	v_mfma_f32_16x16x32_bf16 v[124:127], v[148:151], v[192:195], v[124:127]
	v_mfma_f32_16x16x32_bf16 v[120:123], v[156:159], v[192:195], v[120:123]
	v_mfma_f32_16x16x32_bf16 v[108:111], v[148:151], v[202:205], v[108:111]
	v_mfma_f32_16x16x32_bf16 v[104:107], v[156:159], v[202:205], v[104:107]
	v_mfma_f32_16x16x32_bf16 v[92:95], v[148:151], v[210:213], v[92:95]
	v_mfma_f32_16x16x32_bf16 v[88:91], v[156:159], v[210:213], v[88:91]
	v_mfma_f32_16x16x32_bf16 v[76:79], v[148:151], v[218:221], v[76:79]
	v_mfma_f32_16x16x32_bf16 v[72:75], v[156:159], v[218:221], v[72:75]
	s_setprio 0
	s_setprio 1
	v_mfma_f32_16x16x32_bf16 v[116:119], v[160:163], v[188:191], v[116:119]
	v_mfma_f32_16x16x32_bf16 v[112:115], v[180:183], v[188:191], v[112:115]
	v_mfma_f32_16x16x32_bf16 v[100:103], v[160:163], v[198:201], v[100:103]
	v_mfma_f32_16x16x32_bf16 v[96:99], v[180:183], v[198:201], v[96:99]
	v_mfma_f32_16x16x32_bf16 v[84:87], v[160:163], v[206:209], v[84:87]
	v_mfma_f32_16x16x32_bf16 v[80:83], v[180:183], v[206:209], v[80:83]
	v_mfma_f32_16x16x32_bf16 v[68:71], v[160:163], v[214:217], v[68:71]
	v_mfma_f32_16x16x32_bf16 v[64:67], v[180:183], v[214:217], v[64:67]
	v_mfma_f32_16x16x32_bf16 v[116:119], v[176:179], v[192:195], v[116:119]
	v_mfma_f32_16x16x32_bf16 v[112:115], v[184:187], v[192:195], v[112:115]
	v_mfma_f32_16x16x32_bf16 v[100:103], v[176:179], v[202:205], v[100:103]
	v_mfma_f32_16x16x32_bf16 v[96:99], v[184:187], v[202:205], v[96:99]
	v_mfma_f32_16x16x32_bf16 v[84:87], v[176:179], v[210:213], v[84:87]
	v_mfma_f32_16x16x32_bf16 v[80:83], v[184:187], v[210:213], v[80:83]
	v_mfma_f32_16x16x32_bf16 v[68:71], v[176:179], v[218:221], v[68:71]
	v_mfma_f32_16x16x32_bf16 v[64:67], v[184:187], v[218:221], v[64:67]
	s_setprio 0
	s_barrier
	s_add_i32 s36, s28, s33
	v_lshl_add_u64 v[164:165], s[6:7], 0, v[130:131]
	s_mov_b32 m0, s36
	ds_read_b128 v[188:191], v171 offset:16384
	ds_read_b128 v[192:195], v171 offset:17408
	ds_read_b128 v[198:201], v171 offset:18432
	ds_read_b128 v[202:205], v171 offset:19456
	ds_read_b128 v[206:209], v171 offset:20480
	ds_read_b128 v[210:213], v171 offset:21504
	ds_read_b128 v[214:217], v171 offset:22528
	ds_read_b128 v[218:221], v171 offset:23552
	global_load_lds_dwordx4 v[164:165], off
	s_add_i32 m0, s36, 0x2000
	s_add_u32 s36, s6, 0x40000
	v_lshl_add_u64 v[222:223], s[6:7], 0, v[134:135]
	s_addc_u32 s37, s7, 0
	s_add_i32 s38, s29, s33
	global_load_lds_dwordx4 v[222:223], off
	v_lshl_add_u64 v[224:225], s[36:37], 0, v[130:131]
	s_mov_b32 m0, s38
	v_lshl_add_u64 v[226:227], s[8:9], 0, v[132:133]
	global_load_lds_dwordx4 v[224:225], off
	v_lshl_add_u64 v[224:225], s[36:37], 0, v[134:135]
	s_add_i32 m0, s38, 0x2000
	s_nop 0
	global_load_lds_dwordx4 v[224:225], off
	v_lshl_add_u64 v[224:225], s[8:9], 0, v[128:129]
	s_mov_b32 m0, s77
	s_nop 0
	global_load_lds_dwordx4 v[224:225], off
	s_mov_b32 m0, s62
	s_nop 0
	global_load_lds_dwordx4 v[226:227], off
	s_cmp_lg_u32 s31, -2
	s_cbranch_scc1 .Lfw1a1_st
	s_cmp_eq_u32 s85, 1
	s_cbranch_scc1 .Lfw1a1_st
	s_waitcnt vmcnt(24)
	s_branch .Lfw1a1_dn

; #define PG8_STAGE(bufoff, gbase, voff) do { _Pragma("unroll") for (int _i = 0; _i < 2; ++_i) \
;         __builtin_amdgcn_global_load_lds((const unsigned*)((const char*)(gbase) + (voff)[_i]), (LAS unsigned*)(lds + (bufoff) + ldsw + _i * 8192), 16, 0, 0); } while (0)
; #define PG8_LDA(dst, b, h) do { _Pragma("unroll") for (int m = 0; m < 4; ++m) _Pragma("unroll") for (int k = 0; k < 2; ++k) dst[m][k] = *(const LAS bf16x8*)(lds + PG8_SA(b, h) + aoff + m * 2048 + k * 1024); } while (0)
; #define PG8_LDB(dst, b, h) do { _Pragma("unroll") for (int n = 0; n < 2; ++n) _Pragma("unroll") for (int k = 0; k < 2; ++k) dst[n][k] = *(const LAS bf16x8*)(lds + PG8_SB(b, h) + boff + n * 2048 + k * 1024); } while (0)
; #define PG8_MMA(ai, bj, At, Bt) do { __builtin_amdgcn_s_setprio(1); _Pragma("unroll") for (int m = 0; m < 4; ++m) _Pragma("unroll") for (int n = 0; n < 2; ++n) _Pragma("unroll") for (int k = 0; k < 2; ++k) \
;         acc[ai][bj][m][n] = __builtin_amdgcn_mfma_f32_16x16x32_bf16(Bt[n][k], At[m][k], acc[ai][bj][m][n], 0, 0, 0); __builtin_amdgcn_s_setprio(0); } while (0)
; #define PG8_WAIT_V(n) asm volatile("s_waitcnt vmcnt(" #n ")" ::: "memory")
; #define PG8_WAIT_L(n) asm volatile("s_waitcnt lgkmcnt(" #n ")" ::: "memory")
; #define PG8_BAR __builtin_amdgcn_s_barrier()
; #define PG8_SCHED __builtin_amdgcn_sched_barrier(0)
; template <int KK, class Epi, class Sched, bool ALIGN_EPI = true>
; __device__ __forceinline__ void gemm_phase(LAS unsigned char* lds, const bf16* gA, const bf16* gBt, const Sched& S, const Epi& E, const int wid) {
;     ...
;             PG8_WAIT_V(8); PG8_WAIT_L(0); PG8_BAR; PG8_MMA(1, 0, At, B0); PG8_MMA(1, 1, At, B1); PG8_BAR; PG8_SCHED;
;             PG8_LDB(B0, 1, 0); PG8_LDB(B1, 1, 1); PG8_SCHED; PG8_LDA(At, 1, 0); PG8_STAGE(PG8_SA(0, 1), a2 + hstep, voffA);
;             PG8_WAIT_V(8); PG8_WAIT_L(0); PG8_BAR; PG8_MMA(0, 0, At, B0); PG8_MMA(0, 1, At, B1); PG8_BAR; PG8_SCHED;
.Lfw1a1_dn:
	s_waitcnt lgkmcnt(0)
	s_barrier
	s_setprio 1
	s_waitcnt lgkmcnt(0)
	v_mfma_f32_16x16x32_bf16 v[60:63], v[144:147], v[188:191], v[60:63]
	v_mfma_f32_16x16x32_bf16 v[56:59], v[152:155], v[188:191], v[56:59]
	v_mfma_f32_16x16x32_bf16 v[44:47], v[144:147], v[198:201], v[44:47]
	v_mfma_f32_16x16x32_bf16 v[40:43], v[152:155], v[198:201], v[40:43]
	v_mfma_f32_16x16x32_bf16 v[28:31], v[144:147], v[206:209], v[28:31]
	v_mfma_f32_16x16x32_bf16 v[24:27], v[152:155], v[206:209], v[24:27]
	v_mfma_f32_16x16x32_bf16 v[12:15], v[144:147], v[214:217], v[12:15]
	v_mfma_f32_16x16x32_bf16 v[8:11], v[152:155], v[214:217], v[8:11]
	v_mfma_f32_16x16x32_bf16 v[60:63], v[148:151], v[192:195], v[60:63]
	v_mfma_f32_16x16x32_bf16 v[56:59], v[156:159], v[192:195], v[56:59]
	v_mfma_f32_16x16x32_bf16 v[44:47], v[148:151], v[202:205], v[44:47]
	v_mfma_f32_16x16x32_bf16 v[40:43], v[156:159], v[202:205], v[40:43]
	v_mfma_f32_16x16x32_bf16 v[28:31], v[148:151], v[210:213], v[28:31]
	v_mfma_f32_16x16x32_bf16 v[24:27], v[156:159], v[210:213], v[24:27]
	v_mfma_f32_16x16x32_bf16 v[12:15], v[148:151], v[218:221], v[12:15]
	v_mfma_f32_16x16x32_bf16 v[8:11], v[156:159], v[218:221], v[8:11]
	s_setprio 0
	s_setprio 1
	v_mfma_f32_16x16x32_bf16 v[52:55], v[160:163], v[188:191], v[52:55]
	v_mfma_f32_16x16x32_bf16 v[48:51], v[180:183], v[188:191], v[48:51]
	v_mfma_f32_16x16x32_bf16 v[36:39], v[160:163], v[198:201], v[36:39]
	v_mfma_f32_16x16x32_bf16 v[32:35], v[180:183], v[198:201], v[32:35]
	v_mfma_f32_16x16x32_bf16 v[20:23], v[160:163], v[206:209], v[20:23]
	v_mfma_f32_16x16x32_bf16 v[16:19], v[180:183], v[206:209], v[16:19]
	v_mfma_f32_16x16x32_bf16 v[4:7], v[160:163], v[214:217], v[4:7]
	v_mfma_f32_16x16x32_bf16 v[0:3], v[180:183], v[214:217], v[0:3]
	v_mfma_f32_16x16x32_bf16 v[52:55], v[176:179], v[192:195], v[52:55]
	v_mfma_f32_16x16x32_bf16 v[48:51], v[184:187], v[192:195], v[48:51]
	v_mfma_f32_16x16x32_bf16 v[36:39], v[176:179], v[202:205], v[36:39]
	v_mfma_f32_16x16x32_bf16 v[32:35], v[184:187], v[202:205], v[32:35]
	v_mfma_f32_16x16x32_bf16 v[20:23], v[176:179], v[210:213], v[20:23]
	v_mfma_f32_16x16x32_bf16 v[16:19], v[184:187], v[210:213], v[16:19]
	v_mfma_f32_16x16x32_bf16 v[4:7], v[176:179], v[218:221], v[4:7]
	v_mfma_f32_16x16x32_bf16 v[0:3], v[184:187], v[218:221], v[0:3]
	s_setprio 0
	s_barrier
	ds_read_b128 v[144:147], v172
	ds_read_b128 v[148:151], v172 offset:1024
	ds_read_b128 v[152:155], v172 offset:2048
	ds_read_b128 v[156:159], v172 offset:3072
	ds_read_b128 v[160:163], v173
	ds_read_b128 v[176:179], v173 offset:1024
	ds_read_b128 v[180:183], v173 offset:2048
	ds_read_b128 v[184:187], v173 offset:3072
	s_add_u32 s8, s8, 0x40000
	s_addc_u32 s9, s9, 0
	s_mov_b32 m0, s0
	v_lshl_add_u64 v[228:229], s[8:9], 0, v[128:129]
	ds_read_b128 v[188:191], v171 offset:32768
	ds_read_b128 v[192:195], v171 offset:33792
	ds_read_b128 v[198:201], v171 offset:34816
	ds_read_b128 v[202:205], v171 offset:35840
	ds_read_b128 v[206:209], v171 offset:36864
	ds_read_b128 v[210:213], v171 offset:37888
	ds_read_b128 v[214:217], v171 offset:38912
	ds_read_b128 v[218:221], v171 offset:39936
	global_load_lds_dwordx4 v[228:229], off
	v_lshl_add_u64 v[228:229], s[8:9], 0, v[132:133]
	s_mov_b32 m0, s1
	s_nop 0
	global_load_lds_dwordx4 v[228:229], off
	s_waitcnt vmcnt(8)
	s_waitcnt lgkmcnt(0)
	s_barrier
	s_setprio 1
	s_waitcnt lgkmcnt(0)
	v_mfma_f32_16x16x32_bf16 v[124:127], v[144:147], v[188:191], v[124:127]
	v_mfma_f32_16x16x32_bf16 v[120:123], v[152:155], v[188:191], v[120:123]
	v_mfma_f32_16x16x32_bf16 v[108:111], v[144:147], v[198:201], v[108:111]
	v_mfma_f32_16x16x32_bf16 v[104:107], v[152:155], v[198:201], v[104:107]
	v_mfma_f32_16x16x32_bf16 v[92:95], v[144:147], v[206:209], v[92:95]
	v_mfma_f32_16x16x32_bf16 v[88:91], v[152:155], v[206:209], v[88:91]
	v_mfma_f32_16x16x32_bf16 v[76:79], v[144:147], v[214:217], v[76:79]
	v_mfma_f32_16x16x32_bf16 v[72:75], v[152:155], v[214:217], v[72:75]
	v_mfma_f32_16x16x32_bf16 v[124:127], v[148:151], v[192:195], v[124:127]
	v_mfma_f32_16x16x32_bf16 v[120:123], v[156:159], v[192:195], v[120:123]
	v_mfma_f32_16x16x32_bf16 v[108:111], v[148:151], v[202:205], v[108:111]
	v_mfma_f32_16x16x32_bf16 v[104:107], v[156:159], v[202:205], v[104:107]
	v_mfma_f32_16x16x32_bf16 v[92:95], v[148:151], v[210:213], v[92:95]
	v_mfma_f32_16x16x32_bf16 v[88:91], v[156:159], v[210:213], v[88:91]
	v_mfma_f32_16x16x32_bf16 v[76:79], v[148:151], v[218:221], v[76:79]
	v_mfma_f32_16x16x32_bf16 v[72:75], v[156:159], v[218:221], v[72:75]
	s_setprio 0
	s_setprio 1
	v_mfma_f32_16x16x32_bf16 v[116:119], v[160:163], v[188:191], v[116:119]
	v_mfma_f32_16x16x32_bf16 v[112:115], v[180:183], v[188:191], v[112:115]
	v_mfma_f32_16x16x32_bf16 v[100:103], v[160:163], v[198:201], v[100:103]
	v_mfma_f32_16x16x32_bf16 v[96:99], v[180:183], v[198:201], v[96:99]
	v_mfma_f32_16x16x32_bf16 v[84:87], v[160:163], v[206:209], v[84:87]
	v_mfma_f32_16x16x32_bf16 v[80:83], v[180:183], v[206:209], v[80:83]
	v_mfma_f32_16x16x32_bf16 v[68:71], v[160:163], v[214:217], v[68:71]
	v_mfma_f32_16x16x32_bf16 v[64:67], v[180:183], v[214:217], v[64:67]
	v_mfma_f32_16x16x32_bf16 v[116:119], v[176:179], v[192:195], v[116:119]
	v_mfma_f32_16x16x32_bf16 v[112:115], v[184:187], v[192:195], v[112:115]
	v_mfma_f32_16x16x32_bf16 v[100:103], v[176:179], v[202:205], v[100:103]
	v_mfma_f32_16x16x32_bf16 v[96:99], v[184:187], v[202:205], v[96:99]
	v_mfma_f32_16x16x32_bf16 v[84:87], v[176:179], v[210:213], v[84:87]
	v_mfma_f32_16x16x32_bf16 v[80:83], v[184:187], v[210:213], v[80:83]
	v_mfma_f32_16x16x32_bf16 v[68:71], v[176:179], v[218:221], v[68:71]
	v_mfma_f32_16x16x32_bf16 v[64:67], v[184:187], v[218:221], v[64:67]
	s_setprio 0
	s_barrier
; #define PG8_STAGE(bufoff, gbase, voff) do { _Pragma("unroll") for (int _i = 0; _i < 2; ++_i) \
;         __builtin_amdgcn_global_load_lds((const unsigned*)((const char*)(gbase) + (voff)[_i]), (LAS unsigned*)(lds + (bufoff) + ldsw + _i * 8192), 16, 0, 0); } while (0)
; #define PG8_LDA(dst, b, h) do { _Pragma("unroll") for (int m = 0; m < 4; ++m) _Pragma("unroll") for (int k = 0; k < 2; ++k) dst[m][k] = *(const LAS bf16x8*)(lds + PG8_SA(b, h) + aoff + m * 2048 + k * 1024); } while (0)
; #define PG8_MMA(ai, bj, At, Bt) do { __builtin_amdgcn_s_setprio(1); _Pragma("unroll") for (int m = 0; m < 4; ++m) _Pragma("unroll") for (int n = 0; n < 2; ++n) _Pragma("unroll") for (int k = 0; k < 2; ++k) \
;         acc[ai][bj][m][n] = __builtin_amdgcn_mfma_f32_16x16x32_bf16(Bt[n][k], At[m][k], acc[ai][bj][m][n], 0, 0, 0); __builtin_amdgcn_s_setprio(0); } while (0)
; #define PG8_WAIT_V(n) asm volatile("s_waitcnt vmcnt(" #n ")" ::: "memory")
; #define PG8_WAIT_L(n) asm volatile("s_waitcnt lgkmcnt(" #n ")" ::: "memory")
; #define PG8_BAR __builtin_amdgcn_s_barrier()
; #define PG8_SCHED __builtin_amdgcn_sched_barrier(0)
; template <int KK, class Epi, class Sched, bool ALIGN_EPI = true>
; __device__ __forceinline__ void gemm_phase(LAS unsigned char* lds, const bf16* gA, const bf16* gBt, const Sched& S, const Epi& E, const int wid) {
;     ...
;             PG8_LDA(At, 1, 1); PG8_STAGE(PG8_SB(1, 0), b3, voffB); PG8_STAGE(PG8_SB(1, 1), b3 + hstep, voffB); PG8_STAGE(PG8_SA(1, 0), a3, voffA);
;             PG8_WAIT_V(8); PG8_WAIT_L(0); PG8_BAR; PG8_MMA(1, 0, At, B0); PG8_MMA(1, 1, At, B1); PG8_BAR; PG8_SCHED;
;         }
;         if constexpr (ALIGN_EPI) { if (wr == 0) PG8_BAR; }
	s_add_i32 s8, s61, s33
	v_lshl_add_u64 v[164:165], v[164:165], 0, s[40:41]
	s_mov_b32 m0, s8
	ds_read_b128 v[188:191], v171 offset:49152
	ds_read_b128 v[192:195], v171 offset:50176
	ds_read_b128 v[198:201], v171 offset:51200
	ds_read_b128 v[202:205], v171 offset:52224
	ds_read_b128 v[206:209], v171 offset:53248
	ds_read_b128 v[210:213], v171 offset:54272
	ds_read_b128 v[214:217], v171 offset:55296
	ds_read_b128 v[218:221], v171 offset:56320
	global_load_lds_dwordx4 v[164:165], off
	s_add_i32 m0, s8, 0x2000
	s_add_u32 s6, s6, 0x40080
	v_lshl_add_u64 v[164:165], v[222:223], 0, s[40:41]
	s_addc_u32 s7, s7, 0
	s_add_i32 s8, s60, s33
	global_load_lds_dwordx4 v[164:165], off
	v_lshl_add_u64 v[164:165], s[6:7], 0, v[130:131]
	s_mov_b32 m0, s8
	s_nop 0
	global_load_lds_dwordx4 v[164:165], off
	v_lshl_add_u64 v[164:165], s[6:7], 0, v[134:135]
	s_add_i32 m0, s8, 0x2000
	s_nop 0
	global_load_lds_dwordx4 v[164:165], off
	v_lshl_add_u64 v[164:165], v[224:225], 0, s[40:41]
	s_mov_b32 m0, s63
	s_nop 0
	global_load_lds_dwordx4 v[164:165], off
	v_lshl_add_u64 v[164:165], v[226:227], 0, s[40:41]
	s_mov_b32 m0, s68
	s_nop 0
	global_load_lds_dwordx4 v[164:165], off
	s_waitcnt vmcnt(8)
	s_waitcnt lgkmcnt(0)
	s_barrier
	s_setprio 1
	s_waitcnt lgkmcnt(0)
	v_mfma_f32_16x16x32_bf16 v[60:63], v[144:147], v[188:191], v[60:63]
	v_mfma_f32_16x16x32_bf16 v[56:59], v[152:155], v[188:191], v[56:59]
	v_mfma_f32_16x16x32_bf16 v[44:47], v[144:147], v[198:201], v[44:47]
	v_mfma_f32_16x16x32_bf16 v[40:43], v[152:155], v[198:201], v[40:43]
	v_mfma_f32_16x16x32_bf16 v[28:31], v[144:147], v[206:209], v[28:31]
	v_mfma_f32_16x16x32_bf16 v[24:27], v[152:155], v[206:209], v[24:27]
	v_mfma_f32_16x16x32_bf16 v[12:15], v[144:147], v[214:217], v[12:15]
	v_mfma_f32_16x16x32_bf16 v[8:11], v[152:155], v[214:217], v[8:11]
	v_mfma_f32_16x16x32_bf16 v[60:63], v[148:151], v[192:195], v[60:63]
	v_mfma_f32_16x16x32_bf16 v[56:59], v[156:159], v[192:195], v[56:59]
	v_mfma_f32_16x16x32_bf16 v[44:47], v[148:151], v[202:205], v[44:47]
	v_mfma_f32_16x16x32_bf16 v[40:43], v[156:159], v[202:205], v[40:43]
	v_mfma_f32_16x16x32_bf16 v[28:31], v[148:151], v[210:213], v[28:31]
	v_mfma_f32_16x16x32_bf16 v[24:27], v[156:159], v[210:213], v[24:27]
	v_mfma_f32_16x16x32_bf16 v[12:15], v[148:151], v[218:221], v[12:15]
	v_mfma_f32_16x16x32_bf16 v[8:11], v[156:159], v[218:221], v[8:11]
	s_setprio 0
	s_setprio 1
	v_mfma_f32_16x16x32_bf16 v[52:55], v[160:163], v[188:191], v[52:55]
	v_mfma_f32_16x16x32_bf16 v[48:51], v[180:183], v[188:191], v[48:51]
	v_mfma_f32_16x16x32_bf16 v[36:39], v[160:163], v[198:201], v[36:39]
	v_mfma_f32_16x16x32_bf16 v[32:35], v[180:183], v[198:201], v[32:35]
	v_mfma_f32_16x16x32_bf16 v[20:23], v[160:163], v[206:209], v[20:23]
	v_mfma_f32_16x16x32_bf16 v[16:19], v[180:183], v[206:209], v[16:19]
	v_mfma_f32_16x16x32_bf16 v[4:7], v[160:163], v[214:217], v[4:7]
	v_mfma_f32_16x16x32_bf16 v[0:3], v[180:183], v[214:217], v[0:3]
	v_mfma_f32_16x16x32_bf16 v[52:55], v[176:179], v[192:195], v[52:55]
	v_mfma_f32_16x16x32_bf16 v[48:51], v[184:187], v[192:195], v[48:51]
	v_mfma_f32_16x16x32_bf16 v[36:39], v[176:179], v[202:205], v[36:39]
	v_mfma_f32_16x16x32_bf16 v[32:35], v[184:187], v[202:205], v[32:35]
	v_mfma_f32_16x16x32_bf16 v[20:23], v[176:179], v[210:213], v[20:23]
	v_mfma_f32_16x16x32_bf16 v[16:19], v[184:187], v[210:213], v[16:19]
	v_mfma_f32_16x16x32_bf16 v[4:7], v[176:179], v[218:221], v[4:7]
	v_mfma_f32_16x16x32_bf16 v[0:3], v[184:187], v[218:221], v[0:3]
	s_setprio 0
	s_barrier
	s_add_i32 s31, s31, 2
	s_add_u32 s15, s15, 0x100
	s_addc_u32 s30, s30, 0
	s_add_u32 s4, s4, 0x100
	s_addc_u32 s5, s5, 0
	s_cmp_gt_u32 s31, 13
	s_cbranch_scc0 .LBB0_155
	s_and_b64 vcc, exec, s[72:73]
	s_cbranch_vccz .LBB0_158
	s_barrier

; #define PG8_STAGE(bufoff, gbase, voff) do { _Pragma("unroll") for (int _i = 0; _i < 2; ++_i) \
;         __builtin_amdgcn_global_load_lds((const unsigned*)((const char*)(gbase) + (voff)[_i]), (LAS unsigned*)(lds + (bufoff) + ldsw + _i * 8192), 16, 0, 0); } while (0)
; #define PG8_LDA(dst, b, h) do { _Pragma("unroll") for (int m = 0; m < 4; ++m) _Pragma("unroll") for (int k = 0; k < 2; ++k) dst[m][k] = *(const LAS bf16x8*)(lds + PG8_SA(b, h) + aoff + m * 2048 + k * 1024); } while (0)
; #define PG8_LDB(dst, b, h) do { _Pragma("unroll") for (int n = 0; n < 2; ++n) _Pragma("unroll") for (int k = 0; k < 2; ++k) dst[n][k] = *(const LAS bf16x8*)(lds + PG8_SB(b, h) + boff + n * 2048 + k * 1024); } while (0)
; #define PG8_MMA(ai, bj, At, Bt) do { __builtin_amdgcn_s_setprio(1); _Pragma("unroll") for (int m = 0; m < 4; ++m) _Pragma("unroll") for (int n = 0; n < 2; ++n) _Pragma("unroll") for (int k = 0; k < 2; ++k) \
;         acc[ai][bj][m][n] = __builtin_amdgcn_mfma_f32_16x16x32_bf16(Bt[n][k], At[m][k], acc[ai][bj][m][n], 0, 0, 0); __builtin_amdgcn_s_setprio(0); } while (0)
; #define PG8_WAIT_V(n) asm volatile("s_waitcnt vmcnt(" #n ")" ::: "memory")
; #define PG8_WAIT_L(n) asm volatile("s_waitcnt lgkmcnt(" #n ")" ::: "memory")
; #define PG8_BAR __builtin_amdgcn_s_barrier()
; #define PG8_SCHED __builtin_amdgcn_sched_barrier(0)
; template <int KK, class Epi, class Sched, bool ALIGN_EPI = true>
; __device__ __forceinline__ void gemm_phase(LAS unsigned char* lds, const bf16* gA, const bf16* gBt, const Sched& S, const Epi& E, const int wid) {
;     ...
;         for (int t = 0; t < nt; t += 2) {
;             const bool last = (t == nt - 2);
;             const char* a1 = cA + (size_t)(t + 1) * kstep;
;             const char* a2 = last ? nA : cA + (size_t)(t + 2) * kstep; const char* b2 = last ? nB : cB + (size_t)(t + 2) * kstep;
;             const char* a3 = a2 + kstep; const char* b3 = b2 + kstep;
;             PG8_LDB(B0, 0, 0); PG8_LDB(B1, 0, 1); PG8_SCHED; PG8_LDA(At, 0, 0); PG8_STAGE(PG8_SA(1, 1), a1 + hstep, voffA);
;             PG8_WAIT_V(8); PG8_WAIT_L(0); PG8_BAR; PG8_MMA(0, 0, At, B0); PG8_MMA(0, 1, At, B1); PG8_BAR; PG8_SCHED;
.LBB0_609:
	ds_read_b128 v[140:143], v159
	ds_read_b128 v[144:147], v159 offset:1024
	ds_read_b128 v[148:151], v159 offset:2048
	ds_read_b128 v[152:155], v159 offset:3072
	ds_read_b128 v[166:169], v161
	ds_read_b128 v[170:173], v161 offset:1024
	ds_read_b128 v[174:177], v161 offset:2048
	ds_read_b128 v[178:181], v161 offset:3072
	s_add_u32 s49, s66, 0xfffc0080
	s_addc_u32 s50, s67, -1
	s_cmp_eq_u32 s48, 12
	s_cselect_b32 s79, s15, s50
	s_cselect_b32 s78, s36, s49
	s_cselect_b32 s77, s31, s39
	s_cselect_b32 s76, s37, s38
	v_lshl_add_u64 v[156:157], s[66:67], 0, v[138:139]
	s_add_i32 m0, s29, 0xc000
	ds_read_b128 v[182:185], v162
	ds_read_b128 v[186:189], v162 offset:1024
	ds_read_b128 v[190:193], v162 offset:2048
	ds_read_b128 v[200:203], v162 offset:3072
	ds_read_b128 v[204:207], v162 offset:4096
	ds_read_b128 v[208:211], v162 offset:5120
	ds_read_b128 v[212:215], v162 offset:6144
	ds_read_b128 v[216:219], v162 offset:7168
	global_load_lds_dwordx4 v[156:157], off
	v_lshl_add_u64 v[156:157], s[66:67], 0, v[136:137]
	s_add_i32 m0, s29, 0xe000
	s_nop 0
	global_load_lds_dwordx4 v[156:157], off
	s_cmp_lg_u32 s48, -2
	s_cbranch_scc1 .Lfw4a0_st
	s_cmp_eq_u32 s62, 1
	s_cbranch_scc1 .Lfw4a0_st
	s_waitcnt vmcnt(16)
	s_branch .Lfw4a0_dn

; #define PG8_STAGE(bufoff, gbase, voff) do { _Pragma("unroll") for (int _i = 0; _i < 2; ++_i) \
;         __builtin_amdgcn_global_load_lds((const unsigned*)((const char*)(gbase) + (voff)[_i]), (LAS unsigned*)(lds + (bufoff) + ldsw + _i * 8192), 16, 0, 0); } while (0)
; #define PG8_LDA(dst, b, h) do { _Pragma("unroll") for (int m = 0; m < 4; ++m) _Pragma("unroll") for (int k = 0; k < 2; ++k) dst[m][k] = *(const LAS bf16x8*)(lds + PG8_SA(b, h) + aoff + m * 2048 + k * 1024); } while (0)
; #define PG8_MMA(ai, bj, At, Bt) do { __builtin_amdgcn_s_setprio(1); _Pragma("unroll") for (int m = 0; m < 4; ++m) _Pragma("unroll") for (int n = 0; n < 2; ++n) _Pragma("unroll") for (int k = 0; k < 2; ++k) \
;         acc[ai][bj][m][n] = __builtin_amdgcn_mfma_f32_16x16x32_bf16(Bt[n][k], At[m][k], acc[ai][bj][m][n], 0, 0, 0); __builtin_amdgcn_s_setprio(0); } while (0)
; #define PG8_WAIT_V(n) asm volatile("s_waitcnt vmcnt(" #n ")" ::: "memory")
; #define PG8_WAIT_L(n) asm volatile("s_waitcnt lgkmcnt(" #n ")" ::: "memory")
; #define PG8_BAR __builtin_amdgcn_s_barrier()
; #define PG8_SCHED __builtin_amdgcn_sched_barrier(0)
; template <int KK, class Epi, class Sched, bool ALIGN_EPI = true>
; __device__ __forceinline__ void gemm_phase(LAS unsigned char* lds, const bf16* gA, const bf16* gBt, const Sched& S, const Epi& E, const int wid) {
;     ...
;             PG8_WAIT_V(8); PG8_WAIT_L(0); PG8_BAR; PG8_MMA(0, 0, At, B0); PG8_MMA(0, 1, At, B1); PG8_BAR; PG8_SCHED;
;             PG8_LDA(At, 0, 1); PG8_STAGE(PG8_SB(0, 0), b2, voffB); PG8_STAGE(PG8_SB(0, 1), b2 + hstep, voffB); PG8_STAGE(PG8_SA(0, 0), a2, voffA);
;             PG8_WAIT_V(8); PG8_WAIT_L(0); PG8_BAR; PG8_MMA(1, 0, At, B0); PG8_MMA(1, 1, At, B1); PG8_BAR; PG8_SCHED;
.Lfw4a0_dn:
	s_waitcnt lgkmcnt(0)
	s_barrier
	s_setprio 1
	s_waitcnt lgkmcnt(0)
	v_mfma_f32_16x16x32_bf16 v[124:127], v[140:143], v[182:185], v[124:127]
	v_mfma_f32_16x16x32_bf16 v[116:119], v[148:151], v[182:185], v[116:119]
	v_mfma_f32_16x16x32_bf16 v[108:111], v[140:143], v[190:193], v[108:111]
	v_mfma_f32_16x16x32_bf16 v[100:103], v[148:151], v[190:193], v[100:103]
	v_mfma_f32_16x16x32_bf16 v[92:95], v[140:143], v[204:207], v[92:95]
	v_mfma_f32_16x16x32_bf16 v[84:87], v[148:151], v[204:207], v[84:87]
	v_mfma_f32_16x16x32_bf16 v[76:79], v[140:143], v[212:215], v[76:79]
	v_mfma_f32_16x16x32_bf16 v[68:71], v[148:151], v[212:215], v[68:71]
	v_mfma_f32_16x16x32_bf16 v[124:127], v[144:147], v[186:189], v[124:127]
	v_mfma_f32_16x16x32_bf16 v[116:119], v[152:155], v[186:189], v[116:119]
	v_mfma_f32_16x16x32_bf16 v[108:111], v[144:147], v[200:203], v[108:111]
	v_mfma_f32_16x16x32_bf16 v[100:103], v[152:155], v[200:203], v[100:103]
	v_mfma_f32_16x16x32_bf16 v[92:95], v[144:147], v[208:211], v[92:95]
	v_mfma_f32_16x16x32_bf16 v[84:87], v[152:155], v[208:211], v[84:87]
	v_mfma_f32_16x16x32_bf16 v[76:79], v[144:147], v[216:219], v[76:79]
	v_mfma_f32_16x16x32_bf16 v[68:71], v[152:155], v[216:219], v[68:71]
	s_setprio 0
	s_setprio 1
	v_mfma_f32_16x16x32_bf16 v[120:123], v[166:169], v[182:185], v[120:123]
	v_mfma_f32_16x16x32_bf16 v[112:115], v[174:177], v[182:185], v[112:115]
	v_mfma_f32_16x16x32_bf16 v[104:107], v[166:169], v[190:193], v[104:107]
	v_mfma_f32_16x16x32_bf16 v[96:99], v[174:177], v[190:193], v[96:99]
	v_mfma_f32_16x16x32_bf16 v[88:91], v[166:169], v[204:207], v[88:91]
	v_mfma_f32_16x16x32_bf16 v[80:83], v[174:177], v[204:207], v[80:83]
	v_mfma_f32_16x16x32_bf16 v[72:75], v[166:169], v[212:215], v[72:75]
	v_mfma_f32_16x16x32_bf16 v[64:67], v[174:177], v[212:215], v[64:67]
	v_mfma_f32_16x16x32_bf16 v[120:123], v[170:173], v[186:189], v[120:123]
	v_mfma_f32_16x16x32_bf16 v[112:115], v[178:181], v[186:189], v[112:115]
	v_mfma_f32_16x16x32_bf16 v[104:107], v[170:173], v[200:203], v[104:107]
	v_mfma_f32_16x16x32_bf16 v[96:99], v[178:181], v[200:203], v[96:99]
	v_mfma_f32_16x16x32_bf16 v[88:91], v[170:173], v[208:211], v[88:91]
	v_mfma_f32_16x16x32_bf16 v[80:83], v[178:181], v[208:211], v[80:83]
	v_mfma_f32_16x16x32_bf16 v[72:75], v[170:173], v[216:219], v[72:75]
	v_mfma_f32_16x16x32_bf16 v[64:67], v[178:181], v[216:219], v[64:67]
	s_setprio 0
	s_barrier
	s_add_i32 s49, s63, s33
	v_lshl_add_u64 v[156:157], s[76:77], 0, v[130:131]
	s_mov_b32 m0, s49
	ds_read_b128 v[182:185], v162 offset:16384
	ds_read_b128 v[186:189], v162 offset:17408
	ds_read_b128 v[190:193], v162 offset:18432
	ds_read_b128 v[200:203], v162 offset:19456
	ds_read_b128 v[204:207], v162 offset:20480
	ds_read_b128 v[208:211], v162 offset:21504
	ds_read_b128 v[212:215], v162 offset:22528
	ds_read_b128 v[216:219], v162 offset:23552
	global_load_lds_dwordx4 v[156:157], off
	s_add_i32 m0, s49, 0x2000
	s_add_u32 s50, s76, 0x40000
	v_lshl_add_u64 v[194:195], s[76:77], 0, v[134:135]
	s_addc_u32 s51, s77, 0
	s_add_i32 s49, s68, s33
	global_load_lds_dwordx4 v[194:195], off
	v_lshl_add_u64 v[220:221], s[50:51], 0, v[130:131]
	s_mov_b32 m0, s49
	v_lshl_add_u64 v[222:223], s[78:79], 0, v[132:133]
	global_load_lds_dwordx4 v[220:221], off
	v_lshl_add_u64 v[220:221], s[50:51], 0, v[134:135]
	s_add_i32 m0, s49, 0x2000
	s_nop 0
	global_load_lds_dwordx4 v[220:221], off
	v_lshl_add_u64 v[220:221], s[78:79], 0, v[128:129]
	s_mov_b32 m0, s29
	s_nop 0
	global_load_lds_dwordx4 v[220:221], off
	s_mov_b32 m0, s40
	s_nop 0
	global_load_lds_dwordx4 v[222:223], off
	s_cmp_lg_u32 s48, -2
	s_cbranch_scc1 .Lfw4a1_st
	s_cmp_eq_u32 s62, 1
	s_cbranch_scc1 .Lfw4a1_st
	s_waitcnt vmcnt(16)
	s_branch .Lfw4a1_dn

; #define PG8_STAGE(bufoff, gbase, voff) do { _Pragma("unroll") for (int _i = 0; _i < 2; ++_i) \
;         __builtin_amdgcn_global_load_lds((const unsigned*)((const char*)(gbase) + (voff)[_i]), (LAS unsigned*)(lds + (bufoff) + ldsw + _i * 8192), 16, 0, 0); } while (0)
; #define PG8_LDA(dst, b, h) do { _Pragma("unroll") for (int m = 0; m < 4; ++m) _Pragma("unroll") for (int k = 0; k < 2; ++k) dst[m][k] = *(const LAS bf16x8*)(lds + PG8_SA(b, h) + aoff + m * 2048 + k * 1024); } while (0)
; #define PG8_LDB(dst, b, h) do { _Pragma("unroll") for (int n = 0; n < 2; ++n) _Pragma("unroll") for (int k = 0; k < 2; ++k) dst[n][k] = *(const LAS bf16x8*)(lds + PG8_SB(b, h) + boff + n * 2048 + k * 1024); } while (0)
; #define PG8_MMA(ai, bj, At, Bt) do { __builtin_amdgcn_s_setprio(1); _Pragma("unroll") for (int m = 0; m < 4; ++m) _Pragma("unroll") for (int n = 0; n < 2; ++n) _Pragma("unroll") for (int k = 0; k < 2; ++k) \
;         acc[ai][bj][m][n] = __builtin_amdgcn_mfma_f32_16x16x32_bf16(Bt[n][k], At[m][k], acc[ai][bj][m][n], 0, 0, 0); __builtin_amdgcn_s_setprio(0); } while (0)
; #define PG8_WAIT_V(n) asm volatile("s_waitcnt vmcnt(" #n ")" ::: "memory")
; #define PG8_WAIT_L(n) asm volatile("s_waitcnt lgkmcnt(" #n ")" ::: "memory")
; #define PG8_BAR __builtin_amdgcn_s_barrier()
; #define PG8_SCHED __builtin_amdgcn_sched_barrier(0)
; template <int KK, class Epi, class Sched, bool ALIGN_EPI = true>
; __device__ __forceinline__ void gemm_phase(LAS unsigned char* lds, const bf16* gA, const bf16* gBt, const Sched& S, const Epi& E, const int wid) {
;     ...
;             PG8_WAIT_V(8); PG8_WAIT_L(0); PG8_BAR; PG8_MMA(1, 0, At, B0); PG8_MMA(1, 1, At, B1); PG8_BAR; PG8_SCHED;
;             PG8_LDB(B0, 1, 0); PG8_LDB(B1, 1, 1); PG8_SCHED; PG8_LDA(At, 1, 0); PG8_STAGE(PG8_SA(0, 1), a2 + hstep, voffA);
;             PG8_WAIT_V(8); PG8_WAIT_L(0); PG8_BAR; PG8_MMA(0, 0, At, B0); PG8_MMA(0, 1, At, B1); PG8_BAR; PG8_SCHED;
.Lfw4a1_dn:
	s_waitcnt lgkmcnt(0)
	s_barrier
	s_setprio 1
	s_waitcnt lgkmcnt(0)
	v_mfma_f32_16x16x32_bf16 v[60:63], v[140:143], v[182:185], v[60:63]
	v_mfma_f32_16x16x32_bf16 v[52:55], v[148:151], v[182:185], v[52:55]
	v_mfma_f32_16x16x32_bf16 v[44:47], v[140:143], v[190:193], v[44:47]
	v_mfma_f32_16x16x32_bf16 v[36:39], v[148:151], v[190:193], v[36:39]
	v_mfma_f32_16x16x32_bf16 v[28:31], v[140:143], v[204:207], v[28:31]
	v_mfma_f32_16x16x32_bf16 v[20:23], v[148:151], v[204:207], v[20:23]
	v_mfma_f32_16x16x32_bf16 v[12:15], v[140:143], v[212:215], v[12:15]
	v_mfma_f32_16x16x32_bf16 v[4:7], v[148:151], v[212:215], v[4:7]
	v_mfma_f32_16x16x32_bf16 v[60:63], v[144:147], v[186:189], v[60:63]
	v_mfma_f32_16x16x32_bf16 v[52:55], v[152:155], v[186:189], v[52:55]
	v_mfma_f32_16x16x32_bf16 v[44:47], v[144:147], v[200:203], v[44:47]
	v_mfma_f32_16x16x32_bf16 v[36:39], v[152:155], v[200:203], v[36:39]
	v_mfma_f32_16x16x32_bf16 v[28:31], v[144:147], v[208:211], v[28:31]
	v_mfma_f32_16x16x32_bf16 v[20:23], v[152:155], v[208:211], v[20:23]
	v_mfma_f32_16x16x32_bf16 v[12:15], v[144:147], v[216:219], v[12:15]
	v_mfma_f32_16x16x32_bf16 v[4:7], v[152:155], v[216:219], v[4:7]
	s_setprio 0
	s_setprio 1
	v_mfma_f32_16x16x32_bf16 v[56:59], v[166:169], v[182:185], v[56:59]
	v_mfma_f32_16x16x32_bf16 v[48:51], v[174:177], v[182:185], v[48:51]
	v_mfma_f32_16x16x32_bf16 v[40:43], v[166:169], v[190:193], v[40:43]
	v_mfma_f32_16x16x32_bf16 v[32:35], v[174:177], v[190:193], v[32:35]
	v_mfma_f32_16x16x32_bf16 v[24:27], v[166:169], v[204:207], v[24:27]
	v_mfma_f32_16x16x32_bf16 v[16:19], v[174:177], v[204:207], v[16:19]
	v_mfma_f32_16x16x32_bf16 v[8:11], v[166:169], v[212:215], v[8:11]
	v_mfma_f32_16x16x32_bf16 v[0:3], v[174:177], v[212:215], v[0:3]
	v_mfma_f32_16x16x32_bf16 v[56:59], v[170:173], v[186:189], v[56:59]
	v_mfma_f32_16x16x32_bf16 v[48:51], v[178:181], v[186:189], v[48:51]
	v_mfma_f32_16x16x32_bf16 v[40:43], v[170:173], v[200:203], v[40:43]
	v_mfma_f32_16x16x32_bf16 v[32:35], v[178:181], v[200:203], v[32:35]
	v_mfma_f32_16x16x32_bf16 v[24:27], v[170:173], v[208:211], v[24:27]
	v_mfma_f32_16x16x32_bf16 v[16:19], v[178:181], v[208:211], v[16:19]
	v_mfma_f32_16x16x32_bf16 v[8:11], v[170:173], v[216:219], v[8:11]
	v_mfma_f32_16x16x32_bf16 v[0:3], v[178:181], v[216:219], v[0:3]
	s_setprio 0
	s_barrier
	ds_read_b128 v[140:143], v163
	ds_read_b128 v[144:147], v163 offset:1024
	ds_read_b128 v[148:151], v163 offset:2048
	ds_read_b128 v[152:155], v163 offset:3072
	ds_read_b128 v[166:169], v164
	ds_read_b128 v[170:173], v164 offset:1024
	ds_read_b128 v[174:177], v164 offset:2048
	ds_read_b128 v[178:181], v164 offset:3072
	s_add_u32 s50, s78, 0x40000
	s_addc_u32 s51, s79, 0
	s_mov_b32 m0, s41
	v_lshl_add_u64 v[224:225], s[50:51], 0, v[128:129]
	ds_read_b128 v[182:185], v162 offset:32768
	ds_read_b128 v[186:189], v162 offset:33792
	ds_read_b128 v[190:193], v162 offset:34816
	ds_read_b128 v[200:203], v162 offset:35840
	ds_read_b128 v[204:207], v162 offset:36864
	ds_read_b128 v[208:211], v162 offset:37888
	ds_read_b128 v[212:215], v162 offset:38912
	ds_read_b128 v[216:219], v162 offset:39936
	global_load_lds_dwordx4 v[224:225], off
	v_lshl_add_u64 v[224:225], s[50:51], 0, v[132:133]
	s_mov_b32 m0, s59
	s_nop 0
	global_load_lds_dwordx4 v[224:225], off
	s_waitcnt vmcnt(8)
	s_waitcnt lgkmcnt(0)
	s_barrier
	s_setprio 1
	s_waitcnt lgkmcnt(0)
	v_mfma_f32_16x16x32_bf16 v[124:127], v[140:143], v[182:185], v[124:127]
	v_mfma_f32_16x16x32_bf16 v[116:119], v[148:151], v[182:185], v[116:119]
	v_mfma_f32_16x16x32_bf16 v[108:111], v[140:143], v[190:193], v[108:111]
	v_mfma_f32_16x16x32_bf16 v[100:103], v[148:151], v[190:193], v[100:103]
	v_mfma_f32_16x16x32_bf16 v[92:95], v[140:143], v[204:207], v[92:95]
	v_mfma_f32_16x16x32_bf16 v[84:87], v[148:151], v[204:207], v[84:87]
	v_mfma_f32_16x16x32_bf16 v[76:79], v[140:143], v[212:215], v[76:79]
	v_mfma_f32_16x16x32_bf16 v[68:71], v[148:151], v[212:215], v[68:71]
	v_mfma_f32_16x16x32_bf16 v[124:127], v[144:147], v[186:189], v[124:127]
	v_mfma_f32_16x16x32_bf16 v[116:119], v[152:155], v[186:189], v[116:119]
	v_mfma_f32_16x16x32_bf16 v[108:111], v[144:147], v[200:203], v[108:111]
	v_mfma_f32_16x16x32_bf16 v[100:103], v[152:155], v[200:203], v[100:103]
	v_mfma_f32_16x16x32_bf16 v[92:95], v[144:147], v[208:211], v[92:95]
	v_mfma_f32_16x16x32_bf16 v[84:87], v[152:155], v[208:211], v[84:87]
	v_mfma_f32_16x16x32_bf16 v[76:79], v[144:147], v[216:219], v[76:79]
	v_mfma_f32_16x16x32_bf16 v[68:71], v[152:155], v[216:219], v[68:71]
	s_setprio 0
	s_setprio 1
	v_mfma_f32_16x16x32_bf16 v[120:123], v[166:169], v[182:185], v[120:123]
	v_mfma_f32_16x16x32_bf16 v[112:115], v[174:177], v[182:185], v[112:115]
	v_mfma_f32_16x16x32_bf16 v[104:107], v[166:169], v[190:193], v[104:107]
	v_mfma_f32_16x16x32_bf16 v[96:99], v[174:177], v[190:193], v[96:99]
	v_mfma_f32_16x16x32_bf16 v[88:91], v[166:169], v[204:207], v[88:91]
	v_mfma_f32_16x16x32_bf16 v[80:83], v[174:177], v[204:207], v[80:83]
	v_mfma_f32_16x16x32_bf16 v[72:75], v[166:169], v[212:215], v[72:75]
	v_mfma_f32_16x16x32_bf16 v[64:67], v[174:177], v[212:215], v[64:67]
	v_mfma_f32_16x16x32_bf16 v[120:123], v[170:173], v[186:189], v[120:123]
	v_mfma_f32_16x16x32_bf16 v[112:115], v[178:181], v[186:189], v[112:115]
	v_mfma_f32_16x16x32_bf16 v[104:107], v[170:173], v[200:203], v[104:107]
	v_mfma_f32_16x16x32_bf16 v[96:99], v[178:181], v[200:203], v[96:99]
	v_mfma_f32_16x16x32_bf16 v[88:91], v[170:173], v[208:211], v[88:91]
	v_mfma_f32_16x16x32_bf16 v[80:83], v[178:181], v[208:211], v[80:83]
	v_mfma_f32_16x16x32_bf16 v[72:75], v[170:173], v[216:219], v[72:75]
	v_mfma_f32_16x16x32_bf16 v[64:67], v[178:181], v[216:219], v[64:67]
	s_setprio 0
	s_barrier
; #define PG8_STAGE(bufoff, gbase, voff) do { _Pragma("unroll") for (int _i = 0; _i < 2; ++_i) \
;         __builtin_amdgcn_global_load_lds((const unsigned*)((const char*)(gbase) + (voff)[_i]), (LAS unsigned*)(lds + (bufoff) + ldsw + _i * 8192), 16, 0, 0); } while (0)
; #define PG8_LDA(dst, b, h) do { _Pragma("unroll") for (int m = 0; m < 4; ++m) _Pragma("unroll") for (int k = 0; k < 2; ++k) dst[m][k] = *(const LAS bf16x8*)(lds + PG8_SA(b, h) + aoff + m * 2048 + k * 1024); } while (0)
; #define PG8_MMA(ai, bj, At, Bt) do { __builtin_amdgcn_s_setprio(1); _Pragma("unroll") for (int m = 0; m < 4; ++m) _Pragma("unroll") for (int n = 0; n < 2; ++n) _Pragma("unroll") for (int k = 0; k < 2; ++k) \
;         acc[ai][bj][m][n] = __builtin_amdgcn_mfma_f32_16x16x32_bf16(Bt[n][k], At[m][k], acc[ai][bj][m][n], 0, 0, 0); __builtin_amdgcn_s_setprio(0); } while (0)
; #define PG8_WAIT_V(n) asm volatile("s_waitcnt vmcnt(" #n ")" ::: "memory")
; #define PG8_WAIT_L(n) asm volatile("s_waitcnt lgkmcnt(" #n ")" ::: "memory")
; #define PG8_BAR __builtin_amdgcn_s_barrier()
; #define PG8_SCHED __builtin_amdgcn_sched_barrier(0)
; template <int KK, class Epi, class Sched, bool ALIGN_EPI = true>
; __device__ __forceinline__ void gemm_phase(LAS unsigned char* lds, const bf16* gA, const bf16* gBt, const Sched& S, const Epi& E, const int wid) {
;     ...
;             PG8_LDA(At, 1, 1); PG8_STAGE(PG8_SB(1, 0), b3, voffB); PG8_STAGE(PG8_SB(1, 1), b3 + hstep, voffB); PG8_STAGE(PG8_SA(1, 0), a3, voffA);
;             PG8_WAIT_V(8); PG8_WAIT_L(0); PG8_BAR; PG8_MMA(1, 0, At, B0); PG8_MMA(1, 1, At, B1); PG8_BAR; PG8_SCHED;
;         }
;         if constexpr (ALIGN_EPI) { if (wr == 0) PG8_BAR; }
	s_add_i32 s49, s69, s33
	v_lshl_add_u64 v[156:157], v[156:157], 0, s[6:7]
	s_mov_b32 m0, s49
	ds_read_b128 v[182:185], v162 offset:49152
	ds_read_b128 v[186:189], v162 offset:50176
	ds_read_b128 v[190:193], v162 offset:51200
	ds_read_b128 v[200:203], v162 offset:52224
	ds_read_b128 v[204:207], v162 offset:53248
	ds_read_b128 v[208:211], v162 offset:54272
	ds_read_b128 v[212:215], v162 offset:55296
	ds_read_b128 v[216:219], v162 offset:56320
	global_load_lds_dwordx4 v[156:157], off
	s_add_i32 m0, s49, 0x2000
	s_add_u32 s50, s76, 0x40080
	v_lshl_add_u64 v[156:157], v[194:195], 0, s[6:7]
	s_addc_u32 s51, s77, 0
	s_add_i32 s49, s70, s33
	global_load_lds_dwordx4 v[156:157], off
	v_lshl_add_u64 v[156:157], s[50:51], 0, v[130:131]
	s_mov_b32 m0, s49
	s_nop 0
	global_load_lds_dwordx4 v[156:157], off
	v_lshl_add_u64 v[156:157], s[50:51], 0, v[134:135]
	s_add_i32 m0, s49, 0x2000
	s_nop 0
	global_load_lds_dwordx4 v[156:157], off
	v_lshl_add_u64 v[156:157], v[220:221], 0, s[6:7]
	s_mov_b32 m0, s60
	s_nop 0
	global_load_lds_dwordx4 v[156:157], off
	v_lshl_add_u64 v[156:157], v[222:223], 0, s[6:7]
	s_mov_b32 m0, s61
	s_nop 0
	global_load_lds_dwordx4 v[156:157], off
	s_waitcnt vmcnt(8)
	s_waitcnt lgkmcnt(0)
	s_barrier
	s_setprio 1
	s_waitcnt lgkmcnt(0)
	v_mfma_f32_16x16x32_bf16 v[60:63], v[140:143], v[182:185], v[60:63]
	v_mfma_f32_16x16x32_bf16 v[52:55], v[148:151], v[182:185], v[52:55]
	v_mfma_f32_16x16x32_bf16 v[44:47], v[140:143], v[190:193], v[44:47]
	v_mfma_f32_16x16x32_bf16 v[36:39], v[148:151], v[190:193], v[36:39]
	v_mfma_f32_16x16x32_bf16 v[28:31], v[140:143], v[204:207], v[28:31]
	v_mfma_f32_16x16x32_bf16 v[20:23], v[148:151], v[204:207], v[20:23]
	v_mfma_f32_16x16x32_bf16 v[12:15], v[140:143], v[212:215], v[12:15]
	v_mfma_f32_16x16x32_bf16 v[4:7], v[148:151], v[212:215], v[4:7]
	v_mfma_f32_16x16x32_bf16 v[60:63], v[144:147], v[186:189], v[60:63]
	v_mfma_f32_16x16x32_bf16 v[52:55], v[152:155], v[186:189], v[52:55]
	v_mfma_f32_16x16x32_bf16 v[44:47], v[144:147], v[200:203], v[44:47]
	v_mfma_f32_16x16x32_bf16 v[36:39], v[152:155], v[200:203], v[36:39]
	v_mfma_f32_16x16x32_bf16 v[28:31], v[144:147], v[208:211], v[28:31]
	v_mfma_f32_16x16x32_bf16 v[20:23], v[152:155], v[208:211], v[20:23]
	v_mfma_f32_16x16x32_bf16 v[12:15], v[144:147], v[216:219], v[12:15]
	v_mfma_f32_16x16x32_bf16 v[4:7], v[152:155], v[216:219], v[4:7]
	s_setprio 0
	s_setprio 1
	v_mfma_f32_16x16x32_bf16 v[56:59], v[166:169], v[182:185], v[56:59]
	v_mfma_f32_16x16x32_bf16 v[48:51], v[174:177], v[182:185], v[48:51]
	v_mfma_f32_16x16x32_bf16 v[40:43], v[166:169], v[190:193], v[40:43]
	v_mfma_f32_16x16x32_bf16 v[32:35], v[174:177], v[190:193], v[32:35]
	v_mfma_f32_16x16x32_bf16 v[24:27], v[166:169], v[204:207], v[24:27]
	v_mfma_f32_16x16x32_bf16 v[16:19], v[174:177], v[204:207], v[16:19]
	v_mfma_f32_16x16x32_bf16 v[8:11], v[166:169], v[212:215], v[8:11]
	v_mfma_f32_16x16x32_bf16 v[0:3], v[174:177], v[212:215], v[0:3]
	v_mfma_f32_16x16x32_bf16 v[56:59], v[170:173], v[186:189], v[56:59]
	v_mfma_f32_16x16x32_bf16 v[48:51], v[178:181], v[186:189], v[48:51]
	v_mfma_f32_16x16x32_bf16 v[40:43], v[170:173], v[200:203], v[40:43]
	v_mfma_f32_16x16x32_bf16 v[32:35], v[178:181], v[200:203], v[32:35]
	v_mfma_f32_16x16x32_bf16 v[24:27], v[170:173], v[208:211], v[24:27]
	v_mfma_f32_16x16x32_bf16 v[16:19], v[178:181], v[208:211], v[16:19]
	v_mfma_f32_16x16x32_bf16 v[8:11], v[170:173], v[216:219], v[8:11]
	v_mfma_f32_16x16x32_bf16 v[0:3], v[178:181], v[216:219], v[0:3]
	s_setprio 0
	s_barrier
	s_add_i32 s48, s48, 2
	s_add_u32 s38, s38, 0x100
	s_addc_u32 s39, s39, 0
	s_add_u32 s66, s66, 0x100
	s_addc_u32 s67, s67, 0
	s_cmp_gt_u32 s48, 13
	s_cbranch_scc0 .LBB0_609
	s_and_b64 vcc, exec, s[12:13]
	s_cbranch_vccz .LBB0_612
	s_barrier

; #define PG8_STAGE(bufoff, gbase, voff) do { _Pragma("unroll") for (int _i = 0; _i < 2; ++_i) \
;         __builtin_amdgcn_global_load_lds((const unsigned*)((const char*)(gbase) + (voff)[_i]), (LAS unsigned*)(lds + (bufoff) + ldsw + _i * 8192), 16, 0, 0); } while (0)
; #define PG8_LDA(dst, b, h) do { _Pragma("unroll") for (int m = 0; m < 4; ++m) _Pragma("unroll") for (int k = 0; k < 2; ++k) dst[m][k] = *(const LAS bf16x8*)(lds + PG8_SA(b, h) + aoff + m * 2048 + k * 1024); } while (0)
; #define PG8_LDB(dst, b, h) do { _Pragma("unroll") for (int n = 0; n < 2; ++n) _Pragma("unroll") for (int k = 0; k < 2; ++k) dst[n][k] = *(const LAS bf16x8*)(lds + PG8_SB(b, h) + boff + n * 2048 + k * 1024); } while (0)
; #define PG8_MMA(ai, bj, At, Bt) do { __builtin_amdgcn_s_setprio(1); _Pragma("unroll") for (int m = 0; m < 4; ++m) _Pragma("unroll") for (int n = 0; n < 2; ++n) _Pragma("unroll") for (int k = 0; k < 2; ++k) \
;         acc[ai][bj][m][n] = __builtin_amdgcn_mfma_f32_16x16x32_bf16(Bt[n][k], At[m][k], acc[ai][bj][m][n], 0, 0, 0); __builtin_amdgcn_s_setprio(0); } while (0)
; #define PG8_WAIT_V(n) asm volatile("s_waitcnt vmcnt(" #n ")" ::: "memory")
; #define PG8_WAIT_L(n) asm volatile("s_waitcnt lgkmcnt(" #n ")" ::: "memory")
; #define PG8_BAR __builtin_amdgcn_s_barrier()
; #define PG8_SCHED __builtin_amdgcn_sched_barrier(0)
; template <int KK, class Epi, class Sched, bool ALIGN_EPI = true>
; __device__ __forceinline__ void gemm_phase(LAS unsigned char* lds, const bf16* gA, const bf16* gBt, const Sched& S, const Epi& E, const int wid) {
;     ...
;         for (int t = 0; t < nt; t += 2) {
;             const bool last = (t == nt - 2);
;             const char* a1 = cA + (size_t)(t + 1) * kstep;
;             const char* a2 = last ? nA : cA + (size_t)(t + 2) * kstep; const char* b2 = last ? nB : cB + (size_t)(t + 2) * kstep;
;             const char* a3 = a2 + kstep; const char* b3 = b2 + kstep;
;             PG8_LDB(B0, 0, 0); PG8_LDB(B1, 0, 1); PG8_SCHED; PG8_LDA(At, 0, 0); PG8_STAGE(PG8_SA(1, 1), a1 + hstep, voffA);
;             PG8_WAIT_V(8); PG8_WAIT_L(0); PG8_BAR; PG8_MMA(0, 0, At, B0); PG8_MMA(0, 1, At, B1); PG8_BAR; PG8_SCHED;
.LBB0_903:
	ds_read_b128 v[144:147], v143
	ds_read_b128 v[148:151], v143 offset:1024
	ds_read_b128 v[152:155], v143 offset:2048
	ds_read_b128 v[156:159], v143 offset:3072
	ds_read_b128 v[160:163], v166
	ds_read_b128 v[172:175], v166 offset:1024
	ds_read_b128 v[176:179], v166 offset:2048
	ds_read_b128 v[180:183], v166 offset:3072
	s_add_u32 s8, s6, 0xfffc0080
	s_addc_u32 s9, s7, -1
	s_cmp_eq_u32 s17, 12
	s_cselect_b32 s11, s2, s9
	s_cselect_b32 s10, s3, s8
	s_cselect_b32 s9, s12, s16
	s_cselect_b32 s8, s13, s15
	v_lshl_add_u64 v[164:165], s[6:7], 0, v[140:141]
	s_add_i32 m0, s67, 0xc000
	ds_read_b128 v[184:187], v167
	ds_read_b128 v[188:191], v167 offset:1024
	ds_read_b128 v[192:195], v167 offset:2048
	ds_read_b128 v[200:203], v167 offset:3072
	ds_read_b128 v[204:207], v167 offset:4096
	ds_read_b128 v[208:211], v167 offset:5120
	ds_read_b128 v[212:215], v167 offset:6144
	ds_read_b128 v[216:219], v167 offset:7168
	global_load_lds_dwordx4 v[164:165], off
	v_lshl_add_u64 v[164:165], s[6:7], 0, v[138:139]
	s_add_i32 m0, s67, 0xe000
	s_nop 0
	global_load_lds_dwordx4 v[164:165], off
	s_cmp_lg_u32 s17, -2
	s_cbranch_scc1 .Lfw1b0_st
	s_cmp_eq_u32 s1, 1
	s_cbranch_scc1 .Lfw1b0_st
	s_waitcnt vmcnt(24)
	s_branch .Lfw1b0_dn

; #define PG8_STAGE(bufoff, gbase, voff) do { _Pragma("unroll") for (int _i = 0; _i < 2; ++_i) \
;         __builtin_amdgcn_global_load_lds((const unsigned*)((const char*)(gbase) + (voff)[_i]), (LAS unsigned*)(lds + (bufoff) + ldsw + _i * 8192), 16, 0, 0); } while (0)
; #define PG8_LDA(dst, b, h) do { _Pragma("unroll") for (int m = 0; m < 4; ++m) _Pragma("unroll") for (int k = 0; k < 2; ++k) dst[m][k] = *(const LAS bf16x8*)(lds + PG8_SA(b, h) + aoff + m * 2048 + k * 1024); } while (0)
; #define PG8_MMA(ai, bj, At, Bt) do { __builtin_amdgcn_s_setprio(1); _Pragma("unroll") for (int m = 0; m < 4; ++m) _Pragma("unroll") for (int n = 0; n < 2; ++n) _Pragma("unroll") for (int k = 0; k < 2; ++k) \
;         acc[ai][bj][m][n] = __builtin_amdgcn_mfma_f32_16x16x32_bf16(Bt[n][k], At[m][k], acc[ai][bj][m][n], 0, 0, 0); __builtin_amdgcn_s_setprio(0); } while (0)
; #define PG8_WAIT_V(n) asm volatile("s_waitcnt vmcnt(" #n ")" ::: "memory")
; #define PG8_WAIT_L(n) asm volatile("s_waitcnt lgkmcnt(" #n ")" ::: "memory")
; #define PG8_BAR __builtin_amdgcn_s_barrier()
; #define PG8_SCHED __builtin_amdgcn_sched_barrier(0)
; template <int KK, class Epi, class Sched, bool ALIGN_EPI = true>
; __device__ __forceinline__ void gemm_phase(LAS unsigned char* lds, const bf16* gA, const bf16* gBt, const Sched& S, const Epi& E, const int wid) {
;     ...
;             PG8_WAIT_V(8); PG8_WAIT_L(0); PG8_BAR; PG8_MMA(0, 0, At, B0); PG8_MMA(0, 1, At, B1); PG8_BAR; PG8_SCHED;
;             PG8_LDA(At, 0, 1); PG8_STAGE(PG8_SB(0, 0), b2, voffB); PG8_STAGE(PG8_SB(0, 1), b2 + hstep, voffB); PG8_STAGE(PG8_SA(0, 0), a2, voffA);
;             PG8_WAIT_V(8); PG8_WAIT_L(0); PG8_BAR; PG8_MMA(1, 0, At, B0); PG8_MMA(1, 1, At, B1); PG8_BAR; PG8_SCHED;
.Lfw1b0_dn:
	s_waitcnt lgkmcnt(0)
	s_barrier
	s_setprio 1
	s_waitcnt lgkmcnt(0)
	v_mfma_f32_16x16x32_bf16 v[124:127], v[144:147], v[184:187], v[124:127]
	v_mfma_f32_16x16x32_bf16 v[120:123], v[152:155], v[184:187], v[120:123]
	v_mfma_f32_16x16x32_bf16 v[108:111], v[144:147], v[192:195], v[108:111]
	v_mfma_f32_16x16x32_bf16 v[104:107], v[152:155], v[192:195], v[104:107]
	v_mfma_f32_16x16x32_bf16 v[92:95], v[144:147], v[204:207], v[92:95]
	v_mfma_f32_16x16x32_bf16 v[88:91], v[152:155], v[204:207], v[88:91]
	v_mfma_f32_16x16x32_bf16 v[76:79], v[144:147], v[212:215], v[76:79]
	v_mfma_f32_16x16x32_bf16 v[72:75], v[152:155], v[212:215], v[72:75]
	v_mfma_f32_16x16x32_bf16 v[124:127], v[148:151], v[188:191], v[124:127]
	v_mfma_f32_16x16x32_bf16 v[120:123], v[156:159], v[188:191], v[120:123]
	v_mfma_f32_16x16x32_bf16 v[108:111], v[148:151], v[200:203], v[108:111]
	v_mfma_f32_16x16x32_bf16 v[104:107], v[156:159], v[200:203], v[104:107]
	v_mfma_f32_16x16x32_bf16 v[92:95], v[148:151], v[208:211], v[92:95]
	v_mfma_f32_16x16x32_bf16 v[88:91], v[156:159], v[208:211], v[88:91]
	v_mfma_f32_16x16x32_bf16 v[76:79], v[148:151], v[216:219], v[76:79]
	v_mfma_f32_16x16x32_bf16 v[72:75], v[156:159], v[216:219], v[72:75]
	s_setprio 0
	s_setprio 1
	v_mfma_f32_16x16x32_bf16 v[116:119], v[160:163], v[184:187], v[116:119]
	v_mfma_f32_16x16x32_bf16 v[112:115], v[176:179], v[184:187], v[112:115]
	v_mfma_f32_16x16x32_bf16 v[100:103], v[160:163], v[192:195], v[100:103]
	v_mfma_f32_16x16x32_bf16 v[96:99], v[176:179], v[192:195], v[96:99]
	v_mfma_f32_16x16x32_bf16 v[84:87], v[160:163], v[204:207], v[84:87]
	v_mfma_f32_16x16x32_bf16 v[80:83], v[176:179], v[204:207], v[80:83]
	v_mfma_f32_16x16x32_bf16 v[68:71], v[160:163], v[212:215], v[68:71]
	v_mfma_f32_16x16x32_bf16 v[64:67], v[176:179], v[212:215], v[64:67]
	v_mfma_f32_16x16x32_bf16 v[116:119], v[172:175], v[188:191], v[116:119]
	v_mfma_f32_16x16x32_bf16 v[112:115], v[180:183], v[188:191], v[112:115]
	v_mfma_f32_16x16x32_bf16 v[100:103], v[172:175], v[200:203], v[100:103]
	v_mfma_f32_16x16x32_bf16 v[96:99], v[180:183], v[200:203], v[96:99]
	v_mfma_f32_16x16x32_bf16 v[84:87], v[172:175], v[208:211], v[84:87]
	v_mfma_f32_16x16x32_bf16 v[80:83], v[180:183], v[208:211], v[80:83]
	v_mfma_f32_16x16x32_bf16 v[68:71], v[172:175], v[216:219], v[68:71]
	v_mfma_f32_16x16x32_bf16 v[64:67], v[180:183], v[216:219], v[64:67]
	s_setprio 0
	s_barrier
	s_add_i32 s30, s19, s33
	v_lshl_add_u64 v[164:165], s[8:9], 0, v[130:131]
	s_mov_b32 m0, s30
	ds_read_b128 v[184:187], v167 offset:16384
	ds_read_b128 v[188:191], v167 offset:17408
	ds_read_b128 v[192:195], v167 offset:18432
	ds_read_b128 v[200:203], v167 offset:19456
	ds_read_b128 v[204:207], v167 offset:20480
	ds_read_b128 v[208:211], v167 offset:21504
	ds_read_b128 v[212:215], v167 offset:22528
	ds_read_b128 v[216:219], v167 offset:23552
	global_load_lds_dwordx4 v[164:165], off
	s_add_i32 m0, s30, 0x2000
	s_add_u32 s30, s8, 0x40000
	v_lshl_add_u64 v[220:221], s[8:9], 0, v[134:135]
	s_addc_u32 s31, s9, 0
	s_add_i32 s36, s40, s33
	global_load_lds_dwordx4 v[220:221], off
	v_lshl_add_u64 v[222:223], s[30:31], 0, v[130:131]
	s_mov_b32 m0, s36
	v_lshl_add_u64 v[224:225], s[10:11], 0, v[132:133]
	global_load_lds_dwordx4 v[222:223], off
	v_lshl_add_u64 v[222:223], s[30:31], 0, v[134:135]
	s_add_i32 m0, s36, 0x2000
	s_nop 0
	global_load_lds_dwordx4 v[222:223], off
	v_lshl_add_u64 v[222:223], s[10:11], 0, v[128:129]
	s_mov_b32 m0, s67
	s_nop 0
	global_load_lds_dwordx4 v[222:223], off
	s_mov_b32 m0, s88
	s_nop 0
	global_load_lds_dwordx4 v[224:225], off
	s_cmp_lg_u32 s17, -2
	s_cbranch_scc1 .Lfw1b1_st
	s_cmp_eq_u32 s1, 1
	s_cbranch_scc1 .Lfw1b1_st
	s_waitcnt vmcnt(24)
	s_branch .Lfw1b1_dn

; #define PG8_STAGE(bufoff, gbase, voff) do { _Pragma("unroll") for (int _i = 0; _i < 2; ++_i) \
;         __builtin_amdgcn_global_load_lds((const unsigned*)((const char*)(gbase) + (voff)[_i]), (LAS unsigned*)(lds + (bufoff) + ldsw + _i * 8192), 16, 0, 0); } while (0)
; #define PG8_LDA(dst, b, h) do { _Pragma("unroll") for (int m = 0; m < 4; ++m) _Pragma("unroll") for (int k = 0; k < 2; ++k) dst[m][k] = *(const LAS bf16x8*)(lds + PG8_SA(b, h) + aoff + m * 2048 + k * 1024); } while (0)
; #define PG8_LDB(dst, b, h) do { _Pragma("unroll") for (int n = 0; n < 2; ++n) _Pragma("unroll") for (int k = 0; k < 2; ++k) dst[n][k] = *(const LAS bf16x8*)(lds + PG8_SB(b, h) + boff + n * 2048 + k * 1024); } while (0)
; #define PG8_MMA(ai, bj, At, Bt) do { __builtin_amdgcn_s_setprio(1); _Pragma("unroll") for (int m = 0; m < 4; ++m) _Pragma("unroll") for (int n = 0; n < 2; ++n) _Pragma("unroll") for (int k = 0; k < 2; ++k) \
;         acc[ai][bj][m][n] = __builtin_amdgcn_mfma_f32_16x16x32_bf16(Bt[n][k], At[m][k], acc[ai][bj][m][n], 0, 0, 0); __builtin_amdgcn_s_setprio(0); } while (0)
; #define PG8_WAIT_V(n) asm volatile("s_waitcnt vmcnt(" #n ")" ::: "memory")
; #define PG8_WAIT_L(n) asm volatile("s_waitcnt lgkmcnt(" #n ")" ::: "memory")
; #define PG8_BAR __builtin_amdgcn_s_barrier()
; #define PG8_SCHED __builtin_amdgcn_sched_barrier(0)
; template <int KK, class Epi, class Sched, bool ALIGN_EPI = true>
; __device__ __forceinline__ void gemm_phase(LAS unsigned char* lds, const bf16* gA, const bf16* gBt, const Sched& S, const Epi& E, const int wid) {
;     ...
;             PG8_WAIT_V(8); PG8_WAIT_L(0); PG8_BAR; PG8_MMA(1, 0, At, B0); PG8_MMA(1, 1, At, B1); PG8_BAR; PG8_SCHED;
;             PG8_LDB(B0, 1, 0); PG8_LDB(B1, 1, 1); PG8_SCHED; PG8_LDA(At, 1, 0); PG8_STAGE(PG8_SA(0, 1), a2 + hstep, voffA);
;             PG8_WAIT_V(8); PG8_WAIT_L(0); PG8_BAR; PG8_MMA(0, 0, At, B0); PG8_MMA(0, 1, At, B1); PG8_BAR; PG8_SCHED;
.Lfw1b1_dn:
	s_waitcnt lgkmcnt(0)
	s_barrier
	s_setprio 1
	s_waitcnt lgkmcnt(0)
	v_mfma_f32_16x16x32_bf16 v[60:63], v[144:147], v[184:187], v[60:63]
	v_mfma_f32_16x16x32_bf16 v[56:59], v[152:155], v[184:187], v[56:59]
	v_mfma_f32_16x16x32_bf16 v[44:47], v[144:147], v[192:195], v[44:47]
	v_mfma_f32_16x16x32_bf16 v[40:43], v[152:155], v[192:195], v[40:43]
	v_mfma_f32_16x16x32_bf16 v[28:31], v[144:147], v[204:207], v[28:31]
	v_mfma_f32_16x16x32_bf16 v[24:27], v[152:155], v[204:207], v[24:27]
	v_mfma_f32_16x16x32_bf16 v[12:15], v[144:147], v[212:215], v[12:15]
	v_mfma_f32_16x16x32_bf16 v[8:11], v[152:155], v[212:215], v[8:11]
	v_mfma_f32_16x16x32_bf16 v[60:63], v[148:151], v[188:191], v[60:63]
	v_mfma_f32_16x16x32_bf16 v[56:59], v[156:159], v[188:191], v[56:59]
	v_mfma_f32_16x16x32_bf16 v[44:47], v[148:151], v[200:203], v[44:47]
	v_mfma_f32_16x16x32_bf16 v[40:43], v[156:159], v[200:203], v[40:43]
	v_mfma_f32_16x16x32_bf16 v[28:31], v[148:151], v[208:211], v[28:31]
	v_mfma_f32_16x16x32_bf16 v[24:27], v[156:159], v[208:211], v[24:27]
	v_mfma_f32_16x16x32_bf16 v[12:15], v[148:151], v[216:219], v[12:15]
	v_mfma_f32_16x16x32_bf16 v[8:11], v[156:159], v[216:219], v[8:11]
	s_setprio 0
	s_setprio 1
	v_mfma_f32_16x16x32_bf16 v[52:55], v[160:163], v[184:187], v[52:55]
	v_mfma_f32_16x16x32_bf16 v[48:51], v[176:179], v[184:187], v[48:51]
	v_mfma_f32_16x16x32_bf16 v[36:39], v[160:163], v[192:195], v[36:39]
	v_mfma_f32_16x16x32_bf16 v[32:35], v[176:179], v[192:195], v[32:35]
	v_mfma_f32_16x16x32_bf16 v[20:23], v[160:163], v[204:207], v[20:23]
	v_mfma_f32_16x16x32_bf16 v[16:19], v[176:179], v[204:207], v[16:19]
	v_mfma_f32_16x16x32_bf16 v[4:7], v[160:163], v[212:215], v[4:7]
	v_mfma_f32_16x16x32_bf16 v[0:3], v[176:179], v[212:215], v[0:3]
	v_mfma_f32_16x16x32_bf16 v[52:55], v[172:175], v[188:191], v[52:55]
	v_mfma_f32_16x16x32_bf16 v[48:51], v[180:183], v[188:191], v[48:51]
	v_mfma_f32_16x16x32_bf16 v[36:39], v[172:175], v[200:203], v[36:39]
	v_mfma_f32_16x16x32_bf16 v[32:35], v[180:183], v[200:203], v[32:35]
	v_mfma_f32_16x16x32_bf16 v[20:23], v[172:175], v[208:211], v[20:23]
	v_mfma_f32_16x16x32_bf16 v[16:19], v[180:183], v[208:211], v[16:19]
	v_mfma_f32_16x16x32_bf16 v[4:7], v[172:175], v[216:219], v[4:7]
	v_mfma_f32_16x16x32_bf16 v[0:3], v[180:183], v[216:219], v[0:3]
	s_setprio 0
	s_barrier
	ds_read_b128 v[144:147], v168
	ds_read_b128 v[148:151], v168 offset:1024
	ds_read_b128 v[152:155], v168 offset:2048
	ds_read_b128 v[156:159], v168 offset:3072
	ds_read_b128 v[160:163], v169
	ds_read_b128 v[172:175], v169 offset:1024
	ds_read_b128 v[176:179], v169 offset:2048
	ds_read_b128 v[180:183], v169 offset:3072
	s_add_u32 s10, s10, 0x40000
	s_addc_u32 s11, s11, 0
	s_mov_b32 m0, s89
	v_lshl_add_u64 v[226:227], s[10:11], 0, v[128:129]
	ds_read_b128 v[184:187], v167 offset:32768
	ds_read_b128 v[188:191], v167 offset:33792
	ds_read_b128 v[192:195], v167 offset:34816
	ds_read_b128 v[200:203], v167 offset:35840
	ds_read_b128 v[204:207], v167 offset:36864
	ds_read_b128 v[208:211], v167 offset:37888
	ds_read_b128 v[212:215], v167 offset:38912
	ds_read_b128 v[216:219], v167 offset:39936
	global_load_lds_dwordx4 v[226:227], off
	v_lshl_add_u64 v[226:227], s[10:11], 0, v[132:133]
	s_mov_b32 m0, s74
	s_nop 0
	global_load_lds_dwordx4 v[226:227], off
	s_waitcnt vmcnt(8)
	s_waitcnt lgkmcnt(0)
	s_barrier
	s_setprio 1
	s_waitcnt lgkmcnt(0)
	v_mfma_f32_16x16x32_bf16 v[124:127], v[144:147], v[184:187], v[124:127]
	v_mfma_f32_16x16x32_bf16 v[120:123], v[152:155], v[184:187], v[120:123]
	v_mfma_f32_16x16x32_bf16 v[108:111], v[144:147], v[192:195], v[108:111]
	v_mfma_f32_16x16x32_bf16 v[104:107], v[152:155], v[192:195], v[104:107]
	v_mfma_f32_16x16x32_bf16 v[92:95], v[144:147], v[204:207], v[92:95]
	v_mfma_f32_16x16x32_bf16 v[88:91], v[152:155], v[204:207], v[88:91]
	v_mfma_f32_16x16x32_bf16 v[76:79], v[144:147], v[212:215], v[76:79]
	v_mfma_f32_16x16x32_bf16 v[72:75], v[152:155], v[212:215], v[72:75]
	v_mfma_f32_16x16x32_bf16 v[124:127], v[148:151], v[188:191], v[124:127]
	v_mfma_f32_16x16x32_bf16 v[120:123], v[156:159], v[188:191], v[120:123]
	v_mfma_f32_16x16x32_bf16 v[108:111], v[148:151], v[200:203], v[108:111]
	v_mfma_f32_16x16x32_bf16 v[104:107], v[156:159], v[200:203], v[104:107]
	v_mfma_f32_16x16x32_bf16 v[92:95], v[148:151], v[208:211], v[92:95]
	v_mfma_f32_16x16x32_bf16 v[88:91], v[156:159], v[208:211], v[88:91]
	v_mfma_f32_16x16x32_bf16 v[76:79], v[148:151], v[216:219], v[76:79]
	v_mfma_f32_16x16x32_bf16 v[72:75], v[156:159], v[216:219], v[72:75]
	s_setprio 0
	s_setprio 1
	v_mfma_f32_16x16x32_bf16 v[116:119], v[160:163], v[184:187], v[116:119]
	v_mfma_f32_16x16x32_bf16 v[112:115], v[176:179], v[184:187], v[112:115]
	v_mfma_f32_16x16x32_bf16 v[100:103], v[160:163], v[192:195], v[100:103]
	v_mfma_f32_16x16x32_bf16 v[96:99], v[176:179], v[192:195], v[96:99]
	v_mfma_f32_16x16x32_bf16 v[84:87], v[160:163], v[204:207], v[84:87]
	v_mfma_f32_16x16x32_bf16 v[80:83], v[176:179], v[204:207], v[80:83]
	v_mfma_f32_16x16x32_bf16 v[68:71], v[160:163], v[212:215], v[68:71]
	v_mfma_f32_16x16x32_bf16 v[64:67], v[176:179], v[212:215], v[64:67]
	v_mfma_f32_16x16x32_bf16 v[116:119], v[172:175], v[188:191], v[116:119]
	v_mfma_f32_16x16x32_bf16 v[112:115], v[180:183], v[188:191], v[112:115]
	v_mfma_f32_16x16x32_bf16 v[100:103], v[172:175], v[200:203], v[100:103]
	v_mfma_f32_16x16x32_bf16 v[96:99], v[180:183], v[200:203], v[96:99]
	v_mfma_f32_16x16x32_bf16 v[84:87], v[172:175], v[208:211], v[84:87]
	v_mfma_f32_16x16x32_bf16 v[80:83], v[180:183], v[208:211], v[80:83]
	v_mfma_f32_16x16x32_bf16 v[68:71], v[172:175], v[216:219], v[68:71]
	v_mfma_f32_16x16x32_bf16 v[64:67], v[180:183], v[216:219], v[64:67]
	s_setprio 0
	s_barrier
; #define PG8_STAGE(bufoff, gbase, voff) do { _Pragma("unroll") for (int _i = 0; _i < 2; ++_i) \
;         __builtin_amdgcn_global_load_lds((const unsigned*)((const char*)(gbase) + (voff)[_i]), (LAS unsigned*)(lds + (bufoff) + ldsw + _i * 8192), 16, 0, 0); } while (0)
; #define PG8_LDA(dst, b, h) do { _Pragma("unroll") for (int m = 0; m < 4; ++m) _Pragma("unroll") for (int k = 0; k < 2; ++k) dst[m][k] = *(const LAS bf16x8*)(lds + PG8_SA(b, h) + aoff + m * 2048 + k * 1024); } while (0)
; #define PG8_MMA(ai, bj, At, Bt) do { __builtin_amdgcn_s_setprio(1); _Pragma("unroll") for (int m = 0; m < 4; ++m) _Pragma("unroll") for (int n = 0; n < 2; ++n) _Pragma("unroll") for (int k = 0; k < 2; ++k) \
;         acc[ai][bj][m][n] = __builtin_amdgcn_mfma_f32_16x16x32_bf16(Bt[n][k], At[m][k], acc[ai][bj][m][n], 0, 0, 0); __builtin_amdgcn_s_setprio(0); } while (0)
; #define PG8_WAIT_V(n) asm volatile("s_waitcnt vmcnt(" #n ")" ::: "memory")
; #define PG8_WAIT_L(n) asm volatile("s_waitcnt lgkmcnt(" #n ")" ::: "memory")
; #define PG8_BAR __builtin_amdgcn_s_barrier()
; #define PG8_SCHED __builtin_amdgcn_sched_barrier(0)
; template <int KK, class Epi, class Sched, bool ALIGN_EPI = true>
; __device__ __forceinline__ void gemm_phase(LAS unsigned char* lds, const bf16* gA, const bf16* gBt, const Sched& S, const Epi& E, const int wid) {
;     ...
;             PG8_LDA(At, 1, 1); PG8_STAGE(PG8_SB(1, 0), b3, voffB); PG8_STAGE(PG8_SB(1, 1), b3 + hstep, voffB); PG8_STAGE(PG8_SA(1, 0), a3, voffA);
;             PG8_WAIT_V(8); PG8_WAIT_L(0); PG8_BAR; PG8_MMA(1, 0, At, B0); PG8_MMA(1, 1, At, B1); PG8_BAR; PG8_SCHED;
;         }
;         if constexpr (ALIGN_EPI) { if (wr == 0) PG8_BAR; }
	s_add_i32 s10, s41, s33
	v_lshl_add_u64 v[164:165], v[164:165], 0, s[24:25]
	s_mov_b32 m0, s10
	ds_read_b128 v[184:187], v167 offset:49152
	ds_read_b128 v[188:191], v167 offset:50176
	ds_read_b128 v[192:195], v167 offset:51200
	ds_read_b128 v[200:203], v167 offset:52224
	ds_read_b128 v[204:207], v167 offset:53248
	ds_read_b128 v[208:211], v167 offset:54272
	ds_read_b128 v[212:215], v167 offset:55296
	ds_read_b128 v[216:219], v167 offset:56320
	global_load_lds_dwordx4 v[164:165], off
	s_add_i32 m0, s10, 0x2000
	s_add_u32 s8, s8, 0x40080
	v_lshl_add_u64 v[164:165], v[220:221], 0, s[24:25]
	s_addc_u32 s9, s9, 0
	s_add_i32 s10, s90, s33
	global_load_lds_dwordx4 v[164:165], off
	v_lshl_add_u64 v[164:165], s[8:9], 0, v[130:131]
	s_mov_b32 m0, s10
	s_nop 0
	global_load_lds_dwordx4 v[164:165], off
	v_lshl_add_u64 v[164:165], s[8:9], 0, v[134:135]
	s_add_i32 m0, s10, 0x2000
	s_nop 0
	global_load_lds_dwordx4 v[164:165], off
	v_lshl_add_u64 v[164:165], v[222:223], 0, s[24:25]
	s_mov_b32 m0, s75
	s_nop 0
	global_load_lds_dwordx4 v[164:165], off
	v_lshl_add_u64 v[164:165], v[224:225], 0, s[24:25]
	s_mov_b32 m0, s18
	s_nop 0
	global_load_lds_dwordx4 v[164:165], off
	s_waitcnt vmcnt(8)
	s_waitcnt lgkmcnt(0)
	s_barrier
	s_setprio 1
	s_waitcnt lgkmcnt(0)
	v_mfma_f32_16x16x32_bf16 v[60:63], v[144:147], v[184:187], v[60:63]
	v_mfma_f32_16x16x32_bf16 v[56:59], v[152:155], v[184:187], v[56:59]
	v_mfma_f32_16x16x32_bf16 v[44:47], v[144:147], v[192:195], v[44:47]
	v_mfma_f32_16x16x32_bf16 v[40:43], v[152:155], v[192:195], v[40:43]
	v_mfma_f32_16x16x32_bf16 v[28:31], v[144:147], v[204:207], v[28:31]
	v_mfma_f32_16x16x32_bf16 v[24:27], v[152:155], v[204:207], v[24:27]
	v_mfma_f32_16x16x32_bf16 v[12:15], v[144:147], v[212:215], v[12:15]
	v_mfma_f32_16x16x32_bf16 v[8:11], v[152:155], v[212:215], v[8:11]
	v_mfma_f32_16x16x32_bf16 v[60:63], v[148:151], v[188:191], v[60:63]
	v_mfma_f32_16x16x32_bf16 v[56:59], v[156:159], v[188:191], v[56:59]
	v_mfma_f32_16x16x32_bf16 v[44:47], v[148:151], v[200:203], v[44:47]
	v_mfma_f32_16x16x32_bf16 v[40:43], v[156:159], v[200:203], v[40:43]
	v_mfma_f32_16x16x32_bf16 v[28:31], v[148:151], v[208:211], v[28:31]
	v_mfma_f32_16x16x32_bf16 v[24:27], v[156:159], v[208:211], v[24:27]
	v_mfma_f32_16x16x32_bf16 v[12:15], v[148:151], v[216:219], v[12:15]
	v_mfma_f32_16x16x32_bf16 v[8:11], v[156:159], v[216:219], v[8:11]
	s_setprio 0
	s_setprio 1
	v_mfma_f32_16x16x32_bf16 v[52:55], v[160:163], v[184:187], v[52:55]
	v_mfma_f32_16x16x32_bf16 v[48:51], v[176:179], v[184:187], v[48:51]
	v_mfma_f32_16x16x32_bf16 v[36:39], v[160:163], v[192:195], v[36:39]
	v_mfma_f32_16x16x32_bf16 v[32:35], v[176:179], v[192:195], v[32:35]
	v_mfma_f32_16x16x32_bf16 v[20:23], v[160:163], v[204:207], v[20:23]
	v_mfma_f32_16x16x32_bf16 v[16:19], v[176:179], v[204:207], v[16:19]
	v_mfma_f32_16x16x32_bf16 v[4:7], v[160:163], v[212:215], v[4:7]
	v_mfma_f32_16x16x32_bf16 v[0:3], v[176:179], v[212:215], v[0:3]
	v_mfma_f32_16x16x32_bf16 v[52:55], v[172:175], v[188:191], v[52:55]
	v_mfma_f32_16x16x32_bf16 v[48:51], v[180:183], v[188:191], v[48:51]
	v_mfma_f32_16x16x32_bf16 v[36:39], v[172:175], v[200:203], v[36:39]
	v_mfma_f32_16x16x32_bf16 v[32:35], v[180:183], v[200:203], v[32:35]
	v_mfma_f32_16x16x32_bf16 v[20:23], v[172:175], v[208:211], v[20:23]
	v_mfma_f32_16x16x32_bf16 v[16:19], v[180:183], v[208:211], v[16:19]
	v_mfma_f32_16x16x32_bf16 v[4:7], v[172:175], v[216:219], v[4:7]
	v_mfma_f32_16x16x32_bf16 v[0:3], v[180:183], v[216:219], v[0:3]
	s_setprio 0
	s_barrier
	s_add_i32 s17, s17, 2
	s_add_u32 s15, s15, 0x100
	s_addc_u32 s16, s16, 0
	s_add_u32 s6, s6, 0x100
	s_addc_u32 s7, s7, 0
	s_cmp_gt_u32 s17, 13
	s_cbranch_scc0 .LBB0_903
	s_and_b64 vcc, exec, s[38:39]
	s_cbranch_vccz .LBB0_906
	s_barrier

; #define PG8_STAGE(bufoff, gbase, voff) do { _Pragma("unroll") for (int _i = 0; _i < 2; ++_i) \
;         __builtin_amdgcn_global_load_lds((const unsigned*)((const char*)(gbase) + (voff)[_i]), (LAS unsigned*)(lds + (bufoff) + ldsw + _i * 8192), 16, 0, 0); } while (0)
; #define PG8_LDA(dst, b, h) do { _Pragma("unroll") for (int m = 0; m < 4; ++m) _Pragma("unroll") for (int k = 0; k < 2; ++k) dst[m][k] = *(const LAS bf16x8*)(lds + PG8_SA(b, h) + aoff + m * 2048 + k * 1024); } while (0)
; #define PG8_LDB(dst, b, h) do { _Pragma("unroll") for (int n = 0; n < 2; ++n) _Pragma("unroll") for (int k = 0; k < 2; ++k) dst[n][k] = *(const LAS bf16x8*)(lds + PG8_SB(b, h) + boff + n * 2048 + k * 1024); } while (0)
; #define PG8_MMA(ai, bj, At, Bt) do { __builtin_amdgcn_s_setprio(1); _Pragma("unroll") for (int m = 0; m < 4; ++m) _Pragma("unroll") for (int n = 0; n < 2; ++n) _Pragma("unroll") for (int k = 0; k < 2; ++k) \
;         acc[ai][bj][m][n] = __builtin_amdgcn_mfma_f32_16x16x32_bf16(Bt[n][k], At[m][k], acc[ai][bj][m][n], 0, 0, 0); __builtin_amdgcn_s_setprio(0); } while (0)
; #define PG8_WAIT_V(n) asm volatile("s_waitcnt vmcnt(" #n ")" ::: "memory")
; #define PG8_WAIT_L(n) asm volatile("s_waitcnt lgkmcnt(" #n ")" ::: "memory")
; #define PG8_BAR __builtin_amdgcn_s_barrier()
; #define PG8_SCHED __builtin_amdgcn_sched_barrier(0)
; template <int KK, class Epi, class Sched, bool ALIGN_EPI = true>
; __device__ __forceinline__ void gemm_phase(LAS unsigned char* lds, const bf16* gA, const bf16* gBt, const Sched& S, const Epi& E, const int wid) {
;     ...
;         for (int t = 0; t < nt; t += 2) {
;             const bool last = (t == nt - 2);
;             const char* a1 = cA + (size_t)(t + 1) * kstep;
;             const char* a2 = last ? nA : cA + (size_t)(t + 2) * kstep; const char* b2 = last ? nB : cB + (size_t)(t + 2) * kstep;
;             const char* a3 = a2 + kstep; const char* b3 = b2 + kstep;
;             PG8_LDB(B0, 0, 0); PG8_LDB(B1, 0, 1); PG8_SCHED; PG8_LDA(At, 0, 0); PG8_STAGE(PG8_SA(1, 1), a1 + hstep, voffA);
;             PG8_WAIT_V(8); PG8_WAIT_L(0); PG8_BAR; PG8_MMA(0, 0, At, B0); PG8_MMA(0, 1, At, B1); PG8_BAR; PG8_SCHED;
.LBB0_1246:
	ds_read_b128 v[140:143], v148
	ds_read_b128 v[144:147], v148 offset:1024
	ds_read_b128 v[154:157], v148 offset:2048
	ds_read_b128 v[158:161], v148 offset:3072
	ds_read_b128 v[162:165], v149
	ds_read_b128 v[166:169], v149 offset:1024
	ds_read_b128 v[170:173], v149 offset:2048
	ds_read_b128 v[174:177], v149 offset:3072
	s_add_u32 s44, s42, 0xfffc0080
	s_addc_u32 s45, s43, -1
	s_cmp_eq_u32 s60, 12
	s_cselect_b32 s47, s15, s45
	s_cselect_b32 s46, s55, s44
	s_cselect_b32 s45, s17, s59
	s_cselect_b32 s44, s57, s58
	v_lshl_add_u64 v[194:195], s[42:43], 0, v[138:139]
	s_add_i32 m0, s18, 0xc000
	ds_read_b128 v[178:181], v150
	ds_read_b128 v[182:185], v150 offset:1024
	ds_read_b128 v[186:189], v150 offset:2048
	ds_read_b128 v[190:193], v150 offset:3072
	ds_read_b128 v[200:203], v150 offset:4096
	ds_read_b128 v[204:207], v150 offset:5120
	ds_read_b128 v[208:211], v150 offset:6144
	ds_read_b128 v[212:215], v150 offset:7168
	global_load_lds_dwordx4 v[194:195], off
	v_lshl_add_u64 v[194:195], s[42:43], 0, v[136:137]
	s_add_i32 m0, s18, 0xe000
	s_nop 0
	global_load_lds_dwordx4 v[194:195], off
	s_cmp_lg_u32 s60, -2
	s_cbranch_scc1 .Lfw4b0_st
	s_cmp_eq_u32 s48, 1
	s_cbranch_scc1 .Lfw4b0_st
	s_waitcnt vmcnt(16)
	s_branch .Lfw4b0_dn

; #define PG8_STAGE(bufoff, gbase, voff) do { _Pragma("unroll") for (int _i = 0; _i < 2; ++_i) \
;         __builtin_amdgcn_global_load_lds((const unsigned*)((const char*)(gbase) + (voff)[_i]), (LAS unsigned*)(lds + (bufoff) + ldsw + _i * 8192), 16, 0, 0); } while (0)
; #define PG8_LDA(dst, b, h) do { _Pragma("unroll") for (int m = 0; m < 4; ++m) _Pragma("unroll") for (int k = 0; k < 2; ++k) dst[m][k] = *(const LAS bf16x8*)(lds + PG8_SA(b, h) + aoff + m * 2048 + k * 1024); } while (0)
; #define PG8_MMA(ai, bj, At, Bt) do { __builtin_amdgcn_s_setprio(1); _Pragma("unroll") for (int m = 0; m < 4; ++m) _Pragma("unroll") for (int n = 0; n < 2; ++n) _Pragma("unroll") for (int k = 0; k < 2; ++k) \
;         acc[ai][bj][m][n] = __builtin_amdgcn_mfma_f32_16x16x32_bf16(Bt[n][k], At[m][k], acc[ai][bj][m][n], 0, 0, 0); __builtin_amdgcn_s_setprio(0); } while (0)
; #define PG8_WAIT_V(n) asm volatile("s_waitcnt vmcnt(" #n ")" ::: "memory")
; #define PG8_WAIT_L(n) asm volatile("s_waitcnt lgkmcnt(" #n ")" ::: "memory")
; #define PG8_BAR __builtin_amdgcn_s_barrier()
; #define PG8_SCHED __builtin_amdgcn_sched_barrier(0)
; template <int KK, class Epi, class Sched, bool ALIGN_EPI = true>
; __device__ __forceinline__ void gemm_phase(LAS unsigned char* lds, const bf16* gA, const bf16* gBt, const Sched& S, const Epi& E, const int wid) {
;     ...
;             PG8_WAIT_V(8); PG8_WAIT_L(0); PG8_BAR; PG8_MMA(0, 0, At, B0); PG8_MMA(0, 1, At, B1); PG8_BAR; PG8_SCHED;
;             PG8_LDA(At, 0, 1); PG8_STAGE(PG8_SB(0, 0), b2, voffB); PG8_STAGE(PG8_SB(0, 1), b2 + hstep, voffB); PG8_STAGE(PG8_SA(0, 0), a2, voffA);
;             PG8_WAIT_V(8); PG8_WAIT_L(0); PG8_BAR; PG8_MMA(1, 0, At, B0); PG8_MMA(1, 1, At, B1); PG8_BAR; PG8_SCHED;
.Lfw4b0_dn:
	s_waitcnt lgkmcnt(0)
	s_barrier
	s_setprio 1
	s_waitcnt lgkmcnt(0)
	v_mfma_f32_16x16x32_bf16 v[116:119], v[140:143], v[178:181], v[116:119]
	v_mfma_f32_16x16x32_bf16 v[112:115], v[154:157], v[178:181], v[112:115]
	v_mfma_f32_16x16x32_bf16 v[108:111], v[140:143], v[186:189], v[108:111]
	v_mfma_f32_16x16x32_bf16 v[100:103], v[154:157], v[186:189], v[100:103]
	v_mfma_f32_16x16x32_bf16 v[92:95], v[140:143], v[200:203], v[92:95]
	v_mfma_f32_16x16x32_bf16 v[84:87], v[154:157], v[200:203], v[84:87]
	v_mfma_f32_16x16x32_bf16 v[76:79], v[140:143], v[208:211], v[76:79]
	v_mfma_f32_16x16x32_bf16 v[68:71], v[154:157], v[208:211], v[68:71]
	v_mfma_f32_16x16x32_bf16 v[116:119], v[144:147], v[182:185], v[116:119]
	v_mfma_f32_16x16x32_bf16 v[112:115], v[158:161], v[182:185], v[112:115]
	v_mfma_f32_16x16x32_bf16 v[108:111], v[144:147], v[190:193], v[108:111]
	v_mfma_f32_16x16x32_bf16 v[100:103], v[158:161], v[190:193], v[100:103]
	v_mfma_f32_16x16x32_bf16 v[92:95], v[144:147], v[204:207], v[92:95]
	v_mfma_f32_16x16x32_bf16 v[84:87], v[158:161], v[204:207], v[84:87]
	v_mfma_f32_16x16x32_bf16 v[76:79], v[144:147], v[212:215], v[76:79]
	v_mfma_f32_16x16x32_bf16 v[68:71], v[158:161], v[212:215], v[68:71]
	s_setprio 0
	s_setprio 1
	v_mfma_f32_16x16x32_bf16 v[124:127], v[162:165], v[178:181], v[124:127]
	v_mfma_f32_16x16x32_bf16 v[120:123], v[170:173], v[178:181], v[120:123]
	v_mfma_f32_16x16x32_bf16 v[104:107], v[162:165], v[186:189], v[104:107]
	v_mfma_f32_16x16x32_bf16 v[96:99], v[170:173], v[186:189], v[96:99]
	v_mfma_f32_16x16x32_bf16 v[88:91], v[162:165], v[200:203], v[88:91]
	v_mfma_f32_16x16x32_bf16 v[80:83], v[170:173], v[200:203], v[80:83]
	v_mfma_f32_16x16x32_bf16 v[72:75], v[162:165], v[208:211], v[72:75]
	v_mfma_f32_16x16x32_bf16 v[64:67], v[170:173], v[208:211], v[64:67]
	v_mfma_f32_16x16x32_bf16 v[124:127], v[166:169], v[182:185], v[124:127]
	v_mfma_f32_16x16x32_bf16 v[120:123], v[174:177], v[182:185], v[120:123]
	v_mfma_f32_16x16x32_bf16 v[104:107], v[166:169], v[190:193], v[104:107]
	v_mfma_f32_16x16x32_bf16 v[96:99], v[174:177], v[190:193], v[96:99]
	v_mfma_f32_16x16x32_bf16 v[88:91], v[166:169], v[204:207], v[88:91]
	v_mfma_f32_16x16x32_bf16 v[80:83], v[174:177], v[204:207], v[80:83]
	v_mfma_f32_16x16x32_bf16 v[72:75], v[166:169], v[212:215], v[72:75]
	v_mfma_f32_16x16x32_bf16 v[64:67], v[174:177], v[212:215], v[64:67]
	s_setprio 0
	s_barrier
	s_add_i32 s61, s49, s33
	v_lshl_add_u64 v[194:195], s[44:45], 0, v[130:131]
	s_mov_b32 m0, s61
	ds_read_b128 v[178:181], v150 offset:16384
	ds_read_b128 v[182:185], v150 offset:17408
	ds_read_b128 v[186:189], v150 offset:18432
	ds_read_b128 v[190:193], v150 offset:19456
	ds_read_b128 v[200:203], v150 offset:20480
	ds_read_b128 v[204:207], v150 offset:21504
	ds_read_b128 v[208:211], v150 offset:22528
	ds_read_b128 v[212:215], v150 offset:23552
	global_load_lds_dwordx4 v[194:195], off
	s_add_i32 m0, s61, 0x2000
	s_add_u32 s62, s44, 0x40000
	v_lshl_add_u64 v[216:217], s[44:45], 0, v[134:135]
	s_addc_u32 s63, s45, 0
	s_add_i32 s61, s50, s33
	global_load_lds_dwordx4 v[216:217], off
	v_lshl_add_u64 v[218:219], s[62:63], 0, v[130:131]
	s_mov_b32 m0, s61
	v_lshl_add_u64 v[220:221], s[46:47], 0, v[132:133]
	global_load_lds_dwordx4 v[218:219], off
	v_lshl_add_u64 v[218:219], s[62:63], 0, v[134:135]
	s_add_i32 m0, s61, 0x2000
	s_nop 0
	global_load_lds_dwordx4 v[218:219], off
	v_lshl_add_u64 v[218:219], s[46:47], 0, v[128:129]
	s_mov_b32 m0, s18
	s_nop 0
	global_load_lds_dwordx4 v[218:219], off
	s_mov_b32 m0, s19
	s_nop 0
	global_load_lds_dwordx4 v[220:221], off
	s_cmp_lg_u32 s60, -2
	s_cbranch_scc1 .Lfw4b1_st
	s_cmp_eq_u32 s48, 1
	s_cbranch_scc1 .Lfw4b1_st
	s_waitcnt vmcnt(16)
	s_branch .Lfw4b1_dn

; #define PG8_STAGE(bufoff, gbase, voff) do { _Pragma("unroll") for (int _i = 0; _i < 2; ++_i) \
;         __builtin_amdgcn_global_load_lds((const unsigned*)((const char*)(gbase) + (voff)[_i]), (LAS unsigned*)(lds + (bufoff) + ldsw + _i * 8192), 16, 0, 0); } while (0)
; #define PG8_LDA(dst, b, h) do { _Pragma("unroll") for (int m = 0; m < 4; ++m) _Pragma("unroll") for (int k = 0; k < 2; ++k) dst[m][k] = *(const LAS bf16x8*)(lds + PG8_SA(b, h) + aoff + m * 2048 + k * 1024); } while (0)
; #define PG8_LDB(dst, b, h) do { _Pragma("unroll") for (int n = 0; n < 2; ++n) _Pragma("unroll") for (int k = 0; k < 2; ++k) dst[n][k] = *(const LAS bf16x8*)(lds + PG8_SB(b, h) + boff + n * 2048 + k * 1024); } while (0)
; #define PG8_MMA(ai, bj, At, Bt) do { __builtin_amdgcn_s_setprio(1); _Pragma("unroll") for (int m = 0; m < 4; ++m) _Pragma("unroll") for (int n = 0; n < 2; ++n) _Pragma("unroll") for (int k = 0; k < 2; ++k) \
;         acc[ai][bj][m][n] = __builtin_amdgcn_mfma_f32_16x16x32_bf16(Bt[n][k], At[m][k], acc[ai][bj][m][n], 0, 0, 0); __builtin_amdgcn_s_setprio(0); } while (0)
; #define PG8_WAIT_V(n) asm volatile("s_waitcnt vmcnt(" #n ")" ::: "memory")
; #define PG8_WAIT_L(n) asm volatile("s_waitcnt lgkmcnt(" #n ")" ::: "memory")
; #define PG8_BAR __builtin_amdgcn_s_barrier()
; #define PG8_SCHED __builtin_amdgcn_sched_barrier(0)
; template <int KK, class Epi, class Sched, bool ALIGN_EPI = true>
; __device__ __forceinline__ void gemm_phase(LAS unsigned char* lds, const bf16* gA, const bf16* gBt, const Sched& S, const Epi& E, const int wid) {
;     ...
;             PG8_WAIT_V(8); PG8_WAIT_L(0); PG8_BAR; PG8_MMA(1, 0, At, B0); PG8_MMA(1, 1, At, B1); PG8_BAR; PG8_SCHED;
;             PG8_LDB(B0, 1, 0); PG8_LDB(B1, 1, 1); PG8_SCHED; PG8_LDA(At, 1, 0); PG8_STAGE(PG8_SA(0, 1), a2 + hstep, voffA);
;             PG8_WAIT_V(8); PG8_WAIT_L(0); PG8_BAR; PG8_MMA(0, 0, At, B0); PG8_MMA(0, 1, At, B1); PG8_BAR; PG8_SCHED;
.Lfw4b1_dn:
	s_waitcnt lgkmcnt(0)
	s_barrier
	s_setprio 1
	s_waitcnt lgkmcnt(0)
	v_mfma_f32_16x16x32_bf16 v[60:63], v[140:143], v[178:181], v[60:63]
	v_mfma_f32_16x16x32_bf16 v[52:55], v[154:157], v[178:181], v[52:55]
	v_mfma_f32_16x16x32_bf16 v[44:47], v[140:143], v[186:189], v[44:47]
	v_mfma_f32_16x16x32_bf16 v[36:39], v[154:157], v[186:189], v[36:39]
	v_mfma_f32_16x16x32_bf16 v[28:31], v[140:143], v[200:203], v[28:31]
	v_mfma_f32_16x16x32_bf16 v[20:23], v[154:157], v[200:203], v[20:23]
	v_mfma_f32_16x16x32_bf16 v[12:15], v[140:143], v[208:211], v[12:15]
	v_mfma_f32_16x16x32_bf16 v[4:7], v[154:157], v[208:211], v[4:7]
	v_mfma_f32_16x16x32_bf16 v[60:63], v[144:147], v[182:185], v[60:63]
	v_mfma_f32_16x16x32_bf16 v[52:55], v[158:161], v[182:185], v[52:55]
	v_mfma_f32_16x16x32_bf16 v[44:47], v[144:147], v[190:193], v[44:47]
	v_mfma_f32_16x16x32_bf16 v[36:39], v[158:161], v[190:193], v[36:39]
	v_mfma_f32_16x16x32_bf16 v[28:31], v[144:147], v[204:207], v[28:31]
	v_mfma_f32_16x16x32_bf16 v[20:23], v[158:161], v[204:207], v[20:23]
	v_mfma_f32_16x16x32_bf16 v[12:15], v[144:147], v[212:215], v[12:15]
	v_mfma_f32_16x16x32_bf16 v[4:7], v[158:161], v[212:215], v[4:7]
	s_setprio 0
	s_setprio 1
	v_mfma_f32_16x16x32_bf16 v[56:59], v[162:165], v[178:181], v[56:59]
	v_mfma_f32_16x16x32_bf16 v[48:51], v[170:173], v[178:181], v[48:51]
	v_mfma_f32_16x16x32_bf16 v[40:43], v[162:165], v[186:189], v[40:43]
	v_mfma_f32_16x16x32_bf16 v[32:35], v[170:173], v[186:189], v[32:35]
	v_mfma_f32_16x16x32_bf16 v[24:27], v[162:165], v[200:203], v[24:27]
	v_mfma_f32_16x16x32_bf16 v[16:19], v[170:173], v[200:203], v[16:19]
	v_mfma_f32_16x16x32_bf16 v[8:11], v[162:165], v[208:211], v[8:11]
	v_mfma_f32_16x16x32_bf16 v[0:3], v[170:173], v[208:211], v[0:3]
	v_mfma_f32_16x16x32_bf16 v[56:59], v[166:169], v[182:185], v[56:59]
	v_mfma_f32_16x16x32_bf16 v[48:51], v[174:177], v[182:185], v[48:51]
	v_mfma_f32_16x16x32_bf16 v[40:43], v[166:169], v[190:193], v[40:43]
	v_mfma_f32_16x16x32_bf16 v[32:35], v[174:177], v[190:193], v[32:35]
	v_mfma_f32_16x16x32_bf16 v[24:27], v[166:169], v[204:207], v[24:27]
	v_mfma_f32_16x16x32_bf16 v[16:19], v[174:177], v[204:207], v[16:19]
	v_mfma_f32_16x16x32_bf16 v[8:11], v[166:169], v[212:215], v[8:11]
	v_mfma_f32_16x16x32_bf16 v[0:3], v[174:177], v[212:215], v[0:3]
	s_setprio 0
	s_barrier
	ds_read_b128 v[140:143], v151
	ds_read_b128 v[144:147], v151 offset:1024
	ds_read_b128 v[154:157], v151 offset:2048
	ds_read_b128 v[158:161], v151 offset:3072
	ds_read_b128 v[162:165], v152
	ds_read_b128 v[166:169], v152 offset:1024
	ds_read_b128 v[170:173], v152 offset:2048
	ds_read_b128 v[174:177], v152 offset:3072
	s_add_u32 s46, s46, 0x40000
	s_addc_u32 s47, s47, 0
	s_mov_b32 m0, s37
	v_lshl_add_u64 v[222:223], s[46:47], 0, v[128:129]
	ds_read_b128 v[178:181], v150 offset:32768
	ds_read_b128 v[182:185], v150 offset:33792
	ds_read_b128 v[186:189], v150 offset:34816
	ds_read_b128 v[190:193], v150 offset:35840
	ds_read_b128 v[200:203], v150 offset:36864
	ds_read_b128 v[204:207], v150 offset:37888
	ds_read_b128 v[208:211], v150 offset:38912
	ds_read_b128 v[212:215], v150 offset:39936
	global_load_lds_dwordx4 v[222:223], off
	v_lshl_add_u64 v[222:223], s[46:47], 0, v[132:133]
	s_mov_b32 m0, s39
	s_nop 0
	global_load_lds_dwordx4 v[222:223], off
	s_waitcnt vmcnt(8)
	s_waitcnt lgkmcnt(0)
	s_barrier
	s_setprio 1
	s_waitcnt lgkmcnt(0)
	v_mfma_f32_16x16x32_bf16 v[116:119], v[140:143], v[178:181], v[116:119]
	v_mfma_f32_16x16x32_bf16 v[112:115], v[154:157], v[178:181], v[112:115]
	v_mfma_f32_16x16x32_bf16 v[108:111], v[140:143], v[186:189], v[108:111]
	v_mfma_f32_16x16x32_bf16 v[100:103], v[154:157], v[186:189], v[100:103]
	v_mfma_f32_16x16x32_bf16 v[92:95], v[140:143], v[200:203], v[92:95]
	v_mfma_f32_16x16x32_bf16 v[84:87], v[154:157], v[200:203], v[84:87]
	v_mfma_f32_16x16x32_bf16 v[76:79], v[140:143], v[208:211], v[76:79]
	v_mfma_f32_16x16x32_bf16 v[68:71], v[154:157], v[208:211], v[68:71]
	v_mfma_f32_16x16x32_bf16 v[116:119], v[144:147], v[182:185], v[116:119]
	v_mfma_f32_16x16x32_bf16 v[112:115], v[158:161], v[182:185], v[112:115]
	v_mfma_f32_16x16x32_bf16 v[108:111], v[144:147], v[190:193], v[108:111]
	v_mfma_f32_16x16x32_bf16 v[100:103], v[158:161], v[190:193], v[100:103]
	v_mfma_f32_16x16x32_bf16 v[92:95], v[144:147], v[204:207], v[92:95]
	v_mfma_f32_16x16x32_bf16 v[84:87], v[158:161], v[204:207], v[84:87]
	v_mfma_f32_16x16x32_bf16 v[76:79], v[144:147], v[212:215], v[76:79]
	v_mfma_f32_16x16x32_bf16 v[68:71], v[158:161], v[212:215], v[68:71]
	s_setprio 0
	s_setprio 1
	v_mfma_f32_16x16x32_bf16 v[124:127], v[162:165], v[178:181], v[124:127]
	v_mfma_f32_16x16x32_bf16 v[120:123], v[170:173], v[178:181], v[120:123]
	v_mfma_f32_16x16x32_bf16 v[104:107], v[162:165], v[186:189], v[104:107]
	v_mfma_f32_16x16x32_bf16 v[96:99], v[170:173], v[186:189], v[96:99]
	v_mfma_f32_16x16x32_bf16 v[88:91], v[162:165], v[200:203], v[88:91]
	v_mfma_f32_16x16x32_bf16 v[80:83], v[170:173], v[200:203], v[80:83]
	v_mfma_f32_16x16x32_bf16 v[72:75], v[162:165], v[208:211], v[72:75]
	v_mfma_f32_16x16x32_bf16 v[64:67], v[170:173], v[208:211], v[64:67]
	v_mfma_f32_16x16x32_bf16 v[124:127], v[166:169], v[182:185], v[124:127]
	v_mfma_f32_16x16x32_bf16 v[120:123], v[174:177], v[182:185], v[120:123]
	v_mfma_f32_16x16x32_bf16 v[104:107], v[166:169], v[190:193], v[104:107]
	v_mfma_f32_16x16x32_bf16 v[96:99], v[174:177], v[190:193], v[96:99]
	v_mfma_f32_16x16x32_bf16 v[88:91], v[166:169], v[204:207], v[88:91]
	v_mfma_f32_16x16x32_bf16 v[80:83], v[174:177], v[204:207], v[80:83]
	v_mfma_f32_16x16x32_bf16 v[72:75], v[166:169], v[212:215], v[72:75]
	v_mfma_f32_16x16x32_bf16 v[64:67], v[174:177], v[212:215], v[64:67]
	s_setprio 0
	s_barrier
; #define PG8_STAGE(bufoff, gbase, voff) do { _Pragma("unroll") for (int _i = 0; _i < 2; ++_i) \
;         __builtin_amdgcn_global_load_lds((const unsigned*)((const char*)(gbase) + (voff)[_i]), (LAS unsigned*)(lds + (bufoff) + ldsw + _i * 8192), 16, 0, 0); } while (0)
; #define PG8_LDA(dst, b, h) do { _Pragma("unroll") for (int m = 0; m < 4; ++m) _Pragma("unroll") for (int k = 0; k < 2; ++k) dst[m][k] = *(const LAS bf16x8*)(lds + PG8_SA(b, h) + aoff + m * 2048 + k * 1024); } while (0)
; #define PG8_MMA(ai, bj, At, Bt) do { __builtin_amdgcn_s_setprio(1); _Pragma("unroll") for (int m = 0; m < 4; ++m) _Pragma("unroll") for (int n = 0; n < 2; ++n) _Pragma("unroll") for (int k = 0; k < 2; ++k) \
;         acc[ai][bj][m][n] = __builtin_amdgcn_mfma_f32_16x16x32_bf16(Bt[n][k], At[m][k], acc[ai][bj][m][n], 0, 0, 0); __builtin_amdgcn_s_setprio(0); } while (0)
; #define PG8_WAIT_V(n) asm volatile("s_waitcnt vmcnt(" #n ")" ::: "memory")
; #define PG8_WAIT_L(n) asm volatile("s_waitcnt lgkmcnt(" #n ")" ::: "memory")
; #define PG8_BAR __builtin_amdgcn_s_barrier()
; #define PG8_SCHED __builtin_amdgcn_sched_barrier(0)
; template <int KK, class Epi, class Sched, bool ALIGN_EPI = true>
; __device__ __forceinline__ void gemm_phase(LAS unsigned char* lds, const bf16* gA, const bf16* gBt, const Sched& S, const Epi& E, const int wid) {
;     ...
;             PG8_LDA(At, 1, 1); PG8_STAGE(PG8_SB(1, 0), b3, voffB); PG8_STAGE(PG8_SB(1, 1), b3 + hstep, voffB); PG8_STAGE(PG8_SA(1, 0), a3, voffA);
;             PG8_WAIT_V(8); PG8_WAIT_L(0); PG8_BAR; PG8_MMA(1, 0, At, B0); PG8_MMA(1, 1, At, B1); PG8_BAR; PG8_SCHED;
;         }
;         if constexpr (ALIGN_EPI) { if (wr == 0) PG8_BAR; }
	s_add_i32 s46, s51, s33
	v_lshl_add_u64 v[194:195], v[194:195], 0, s[6:7]
	s_mov_b32 m0, s46
	ds_read_b128 v[178:181], v150 offset:49152
	ds_read_b128 v[182:185], v150 offset:50176
	ds_read_b128 v[186:189], v150 offset:51200
	ds_read_b128 v[190:193], v150 offset:52224
	ds_read_b128 v[200:203], v150 offset:53248
	ds_read_b128 v[204:207], v150 offset:54272
	ds_read_b128 v[208:211], v150 offset:55296
	ds_read_b128 v[212:215], v150 offset:56320
	global_load_lds_dwordx4 v[194:195], off
	s_add_i32 m0, s46, 0x2000
	s_add_u32 s44, s44, 0x40080
	v_lshl_add_u64 v[194:195], v[216:217], 0, s[6:7]
	s_addc_u32 s45, s45, 0
	s_add_i32 s46, s52, s33
	global_load_lds_dwordx4 v[194:195], off
	v_lshl_add_u64 v[194:195], s[44:45], 0, v[130:131]
	s_mov_b32 m0, s46
	s_nop 0
	global_load_lds_dwordx4 v[194:195], off
	v_lshl_add_u64 v[194:195], s[44:45], 0, v[134:135]
	s_add_i32 m0, s46, 0x2000
	s_nop 0
	global_load_lds_dwordx4 v[194:195], off
	v_lshl_add_u64 v[194:195], v[218:219], 0, s[6:7]
	s_mov_b32 m0, s40
	s_nop 0
	global_load_lds_dwordx4 v[194:195], off
	v_lshl_add_u64 v[194:195], v[220:221], 0, s[6:7]
	s_mov_b32 m0, s41
	s_nop 0
	global_load_lds_dwordx4 v[194:195], off
	s_waitcnt vmcnt(8)
	s_waitcnt lgkmcnt(0)
	s_barrier
	s_setprio 1
	s_waitcnt lgkmcnt(0)
	v_mfma_f32_16x16x32_bf16 v[60:63], v[140:143], v[178:181], v[60:63]
	v_mfma_f32_16x16x32_bf16 v[52:55], v[154:157], v[178:181], v[52:55]
	v_mfma_f32_16x16x32_bf16 v[44:47], v[140:143], v[186:189], v[44:47]
	v_mfma_f32_16x16x32_bf16 v[36:39], v[154:157], v[186:189], v[36:39]
	v_mfma_f32_16x16x32_bf16 v[28:31], v[140:143], v[200:203], v[28:31]
	v_mfma_f32_16x16x32_bf16 v[20:23], v[154:157], v[200:203], v[20:23]
	v_mfma_f32_16x16x32_bf16 v[12:15], v[140:143], v[208:211], v[12:15]
	v_mfma_f32_16x16x32_bf16 v[4:7], v[154:157], v[208:211], v[4:7]
	v_mfma_f32_16x16x32_bf16 v[60:63], v[144:147], v[182:185], v[60:63]
	v_mfma_f32_16x16x32_bf16 v[52:55], v[158:161], v[182:185], v[52:55]
	v_mfma_f32_16x16x32_bf16 v[44:47], v[144:147], v[190:193], v[44:47]
	v_mfma_f32_16x16x32_bf16 v[36:39], v[158:161], v[190:193], v[36:39]
	v_mfma_f32_16x16x32_bf16 v[28:31], v[144:147], v[204:207], v[28:31]
	v_mfma_f32_16x16x32_bf16 v[20:23], v[158:161], v[204:207], v[20:23]
	v_mfma_f32_16x16x32_bf16 v[12:15], v[144:147], v[212:215], v[12:15]
	v_mfma_f32_16x16x32_bf16 v[4:7], v[158:161], v[212:215], v[4:7]
	s_setprio 0
	s_setprio 1
	v_mfma_f32_16x16x32_bf16 v[56:59], v[162:165], v[178:181], v[56:59]
	v_mfma_f32_16x16x32_bf16 v[48:51], v[170:173], v[178:181], v[48:51]
	v_mfma_f32_16x16x32_bf16 v[40:43], v[162:165], v[186:189], v[40:43]
	v_mfma_f32_16x16x32_bf16 v[32:35], v[170:173], v[186:189], v[32:35]
	v_mfma_f32_16x16x32_bf16 v[24:27], v[162:165], v[200:203], v[24:27]
	v_mfma_f32_16x16x32_bf16 v[16:19], v[170:173], v[200:203], v[16:19]
	v_mfma_f32_16x16x32_bf16 v[8:11], v[162:165], v[208:211], v[8:11]
	v_mfma_f32_16x16x32_bf16 v[0:3], v[170:173], v[208:211], v[0:3]
	v_mfma_f32_16x16x32_bf16 v[56:59], v[166:169], v[182:185], v[56:59]
	v_mfma_f32_16x16x32_bf16 v[48:51], v[174:177], v[182:185], v[48:51]
	v_mfma_f32_16x16x32_bf16 v[40:43], v[166:169], v[190:193], v[40:43]
	v_mfma_f32_16x16x32_bf16 v[32:35], v[174:177], v[190:193], v[32:35]
	v_mfma_f32_16x16x32_bf16 v[24:27], v[166:169], v[204:207], v[24:27]
	v_mfma_f32_16x16x32_bf16 v[16:19], v[174:177], v[204:207], v[16:19]
	v_mfma_f32_16x16x32_bf16 v[8:11], v[166:169], v[212:215], v[8:11]
	v_mfma_f32_16x16x32_bf16 v[0:3], v[174:177], v[212:215], v[0:3]
	s_setprio 0
	s_barrier
	s_add_i32 s60, s60, 2
	s_add_u32 s58, s58, 0x100
	s_addc_u32 s59, s59, 0
	s_add_u32 s42, s42, 0x100
	s_addc_u32 s43, s43, 0
	s_cmp_gt_u32 s60, 13
	s_cbranch_scc0 .LBB0_1246
	s_and_b64 vcc, exec, s[10:11]
	s_cbranch_vccz .LBB0_1249
	s_barrier
